# v24: forget-gate cumsums computed once in M1 and passed to M3 via f32 workspace (M3 no longer recomputes gates/prefix)
# speedup vs baseline: 1.0124x; 1.0124x over previous
; template <class Epi, class Sched, bool ALIGN_EPI = false, bool SP2 = false>
; __device__ __forceinline__ void gemm_phase(PG8_LAS unsigned char* lds, const Gemm g, const Sched& S, const Epi& E) {
;     ...
;         const char* nA = has_next ? (const char*)g.A + (size_t)nxt.pm * tstep + (size_t)nxt.kt0 * kstep : cA; const char* nB = has_next ? (const char*)g.Bt + (size_t)nxt.pn * tstep + (size_t)nxt.kt0 * kstep : cB;
;     ...
;         for (int a = 0; a < 2; ++a)
; #pragma unroll
;             for (int b = 0; b < 2; ++b)
; #pragma unroll
;                 for (int m = 0; m < 4; ++m)
; #pragma unroll
;                     for (int n = 0; n < 2; ++n) acc[a][b][m][n] = (f32x4){0.f, 0.f, 0.f, 0.f};
;         cur = nxt; cA = nA; cB = nB; ++ui;
.LBB0_293:
	s_ashr_i32 s17, s16, 31
	s_lshl_b64 s[18:19], s[16:17], 19
	s_add_u32 s18, s0, s18
	s_addc_u32 s19, s28, s19
	s_and_b64 s[20:21], s[4:5], exec
	s_cselect_b32 s17, s19, s25
	s_cselect_b32 s42, s18, s24
	s_ashr_i32 s15, s14, 31
	s_lshl_b64 s[20:21], s[14:15], 19
	s_add_u32 s20, s29, s20
	s_addc_u32 s21, s30, s21
	s_and_b64 s[26:27], s[4:5], exec
	s_cselect_b32 s15, s21, s3
	s_cselect_b32 s43, s20, s2
	s_add_u32 s45, s2, 0x100
	s_addc_u32 s46, s3, 0
	s_add_u32 s2, s24, 0x40080
	v_mov_b32_e32 v0, 0
	s_addc_u32 s3, s25, 0
	s_mov_b32 s47, -2
	v_mov_b64_e32 v[0:1], 0
	v_mov_b64_e32 v[2:3], 0
	v_mov_b64_e32 v[8:9], 0
	v_mov_b64_e32 v[10:11], 0
	v_mov_b64_e32 v[16:17], 0
	v_mov_b64_e32 v[18:19], 0
	v_mov_b64_e32 v[24:25], 0
	v_mov_b64_e32 v[26:27], 0
	v_mov_b64_e32 v[32:33], 0
	v_mov_b64_e32 v[34:35], 0
	v_mov_b64_e32 v[40:41], 0
	v_mov_b64_e32 v[42:43], 0
	v_mov_b64_e32 v[48:49], 0
	v_mov_b64_e32 v[50:51], 0
	v_mov_b64_e32 v[56:57], 0
	v_mov_b64_e32 v[58:59], 0
	v_mov_b64_e32 v[4:5], 0
	v_mov_b64_e32 v[6:7], 0
	v_mov_b64_e32 v[12:13], 0
	v_mov_b64_e32 v[14:15], 0
	v_mov_b64_e32 v[20:21], 0
	v_mov_b64_e32 v[22:23], 0
	v_mov_b64_e32 v[28:29], 0
	v_mov_b64_e32 v[30:31], 0
	v_mov_b64_e32 v[36:37], 0
	v_mov_b64_e32 v[38:39], 0
	v_mov_b64_e32 v[44:45], 0
	v_mov_b64_e32 v[46:47], 0
	v_mov_b64_e32 v[52:53], 0
	v_mov_b64_e32 v[54:55], 0
	v_mov_b64_e32 v[60:61], 0
	v_mov_b64_e32 v[62:63], 0
	v_mov_b64_e32 v[64:65], 0
	v_mov_b64_e32 v[66:67], 0
	v_mov_b64_e32 v[72:73], 0
	v_mov_b64_e32 v[74:75], 0
	v_mov_b64_e32 v[80:81], 0
	v_mov_b64_e32 v[82:83], 0
	v_mov_b64_e32 v[88:89], 0
	v_mov_b64_e32 v[90:91], 0
	v_mov_b64_e32 v[96:97], 0
	v_mov_b64_e32 v[98:99], 0
	v_mov_b64_e32 v[104:105], 0
	v_mov_b64_e32 v[106:107], 0
	v_mov_b64_e32 v[112:113], 0
	v_mov_b64_e32 v[114:115], 0
	v_mov_b64_e32 v[120:121], 0
	v_mov_b64_e32 v[122:123], 0
	v_mov_b64_e32 v[68:69], 0
	v_mov_b64_e32 v[70:71], 0
	v_mov_b64_e32 v[76:77], 0
	v_mov_b64_e32 v[78:79], 0
	v_mov_b64_e32 v[84:85], 0
	v_mov_b64_e32 v[86:87], 0
	v_mov_b64_e32 v[92:93], 0
	v_mov_b64_e32 v[94:95], 0
	v_mov_b64_e32 v[100:101], 0
	v_mov_b64_e32 v[102:103], 0
	v_mov_b64_e32 v[108:109], 0
	v_mov_b64_e32 v[110:111], 0
	v_mov_b64_e32 v[116:117], 0
	v_mov_b64_e32 v[118:119], 0
	v_mov_b64_e32 v[124:125], 0
	v_mov_b64_e32 v[126:127], 0
	s_mov_b64 s[52:53], 0x80

; template <class Epi, class Sched, bool ALIGN_EPI = false, bool SP2 = false>
; __device__ __forceinline__ void gemm_phase(PG8_LAS unsigned char* lds, const Gemm g, const Sched& S, const Epi& E) {
;     ...
;         for (int a = 0; a < 2; ++a)
; #pragma unroll
;             for (int b = 0; b < 2; ++b)
; #pragma unroll
;                 for (int m = 0; m < 4; ++m)
; #pragma unroll
;                     for (int n = 0; n < 2; ++n) acc[a][b][m][n] = (f32x4){0.f, 0.f, 0.f, 0.f};
.LBB0_376:
	s_add_i32 s25, s27, -2
	s_add_u32 s58, s34, 0x100
	v_mov_b32_e32 v0, 0
	s_addc_u32 s59, s35, 0
	s_mov_b32 s34, 0
	v_mov_b64_e32 v[0:1], 0
	v_mov_b64_e32 v[2:3], 0
	v_mov_b64_e32 v[4:5], 0
	v_mov_b64_e32 v[6:7], 0
	v_mov_b64_e32 v[8:9], 0
	v_mov_b64_e32 v[10:11], 0
	v_mov_b64_e32 v[12:13], 0
	v_mov_b64_e32 v[14:15], 0
	v_mov_b64_e32 v[16:17], 0
	v_mov_b64_e32 v[18:19], 0
	v_mov_b64_e32 v[20:21], 0
	v_mov_b64_e32 v[22:23], 0
	v_mov_b64_e32 v[24:25], 0
	v_mov_b64_e32 v[26:27], 0
	v_mov_b64_e32 v[28:29], 0
	v_mov_b64_e32 v[30:31], 0
	v_mov_b64_e32 v[32:33], 0
	v_mov_b64_e32 v[34:35], 0
	v_mov_b64_e32 v[36:37], 0
	v_mov_b64_e32 v[38:39], 0
	v_mov_b64_e32 v[40:41], 0
	v_mov_b64_e32 v[42:43], 0
	v_mov_b64_e32 v[44:45], 0
	v_mov_b64_e32 v[46:47], 0
	v_mov_b64_e32 v[48:49], 0
	v_mov_b64_e32 v[50:51], 0
	v_mov_b64_e32 v[52:53], 0
	v_mov_b64_e32 v[54:55], 0
	v_mov_b64_e32 v[56:57], 0
	v_mov_b64_e32 v[58:59], 0
	v_mov_b64_e32 v[60:61], 0
	v_mov_b64_e32 v[62:63], 0
	v_mov_b64_e32 v[64:65], 0
	v_mov_b64_e32 v[66:67], 0
	v_mov_b64_e32 v[68:69], 0
	v_mov_b64_e32 v[70:71], 0
	v_mov_b64_e32 v[72:73], 0
	v_mov_b64_e32 v[74:75], 0
	v_mov_b64_e32 v[76:77], 0
	v_mov_b64_e32 v[78:79], 0
	v_mov_b64_e32 v[80:81], 0
	v_mov_b64_e32 v[82:83], 0
	v_mov_b64_e32 v[84:85], 0
	v_mov_b64_e32 v[86:87], 0
	v_mov_b64_e32 v[88:89], 0
	v_mov_b64_e32 v[90:91], 0
	v_mov_b64_e32 v[92:93], 0
	v_mov_b64_e32 v[94:95], 0
	v_mov_b64_e32 v[96:97], 0
	v_mov_b64_e32 v[98:99], 0
	v_mov_b64_e32 v[100:101], 0
	v_mov_b64_e32 v[102:103], 0
	v_mov_b64_e32 v[104:105], 0
	v_mov_b64_e32 v[106:107], 0
	v_mov_b64_e32 v[108:109], 0
	v_mov_b64_e32 v[110:111], 0
	v_mov_b64_e32 v[112:113], 0
	v_mov_b64_e32 v[114:115], 0
	v_mov_b64_e32 v[116:117], 0
	v_mov_b64_e32 v[118:119], 0
	v_mov_b64_e32 v[120:121], 0
	v_mov_b64_e32 v[122:123], 0
	v_mov_b64_e32 v[124:125], 0
	v_mov_b64_e32 v[126:127], 0
	s_mov_b64 s[66:67], 0x80

; template <class Epi, class Sched, bool ALIGN_EPI = false, bool SP2 = false>
; __device__ __forceinline__ void gemm_phase(PG8_LAS unsigned char* lds, const Gemm g, const Sched& S, const Epi& E) {
;     ...
;         for (int a = 0; a < 2; ++a)
; #pragma unroll
;             for (int b = 0; b < 2; ++b)
; #pragma unroll
;                 for (int m = 0; m < 4; ++m)
; #pragma unroll
;                     for (int n = 0; n < 2; ++n) acc[a][b][m][n] = (f32x4){0.f, 0.f, 0.f, 0.f};
.LBB0_393:
	v_mov_b32_e32 v127, 0
	v_mov_b64_e32 v[126:127], 0
	v_mov_b64_e32 v[124:125], 0
	v_mov_b64_e32 v[122:123], 0
	v_mov_b64_e32 v[120:121], 0
	v_mov_b64_e32 v[118:119], 0
	v_mov_b64_e32 v[116:117], 0
	v_mov_b64_e32 v[114:115], 0
	v_mov_b64_e32 v[112:113], 0
	v_mov_b64_e32 v[110:111], 0
	v_mov_b64_e32 v[108:109], 0
	v_mov_b64_e32 v[106:107], 0
	v_mov_b64_e32 v[104:105], 0
	v_mov_b64_e32 v[102:103], 0
	v_mov_b64_e32 v[100:101], 0
	v_mov_b64_e32 v[98:99], 0
	v_mov_b64_e32 v[96:97], 0
	v_mov_b64_e32 v[94:95], 0
	v_mov_b64_e32 v[92:93], 0
	v_mov_b64_e32 v[90:91], 0
	v_mov_b64_e32 v[88:89], 0
	v_mov_b64_e32 v[86:87], 0
	v_mov_b64_e32 v[84:85], 0
	v_mov_b64_e32 v[82:83], 0
	v_mov_b64_e32 v[80:81], 0
	v_mov_b64_e32 v[78:79], 0
	v_mov_b64_e32 v[76:77], 0
	v_mov_b64_e32 v[74:75], 0
	v_mov_b64_e32 v[72:73], 0
	v_mov_b64_e32 v[70:71], 0
	v_mov_b64_e32 v[68:69], 0
	v_mov_b64_e32 v[66:67], 0
	v_mov_b64_e32 v[64:65], 0
	v_mov_b64_e32 v[62:63], 0
	v_mov_b64_e32 v[60:61], 0
	v_mov_b64_e32 v[58:59], 0
	v_mov_b64_e32 v[56:57], 0
	v_mov_b64_e32 v[54:55], 0
	v_mov_b64_e32 v[52:53], 0
	v_mov_b64_e32 v[50:51], 0
	v_mov_b64_e32 v[48:49], 0
	v_mov_b64_e32 v[46:47], 0
	v_mov_b64_e32 v[44:45], 0
	v_mov_b64_e32 v[42:43], 0
	v_mov_b64_e32 v[40:41], 0
	v_mov_b64_e32 v[38:39], 0
	v_mov_b64_e32 v[36:37], 0
	v_mov_b64_e32 v[34:35], 0
	v_mov_b64_e32 v[32:33], 0
	v_mov_b64_e32 v[30:31], 0
	v_mov_b64_e32 v[28:29], 0
	v_mov_b64_e32 v[26:27], 0
	v_mov_b64_e32 v[24:25], 0
	v_mov_b64_e32 v[22:23], 0
	v_mov_b64_e32 v[20:21], 0
	v_mov_b64_e32 v[18:19], 0
	v_mov_b64_e32 v[16:17], 0
	v_mov_b64_e32 v[14:15], 0
	v_mov_b64_e32 v[12:13], 0
	v_mov_b64_e32 v[10:11], 0
	v_mov_b64_e32 v[8:9], 0
	v_mov_b64_e32 v[6:7], 0
	v_mov_b64_e32 v[4:5], 0
	v_mov_b64_e32 v[2:3], 0
	v_mov_b64_e32 v[0:1], 0
	s_and_b64 vcc, exec, s[18:19]
	s_cbranch_vccnz .LBB0_379
	s_branch .LBB0_380

; template <class Epi, class Sched, bool ALIGN_EPI = false, bool SP2 = false>
; __device__ __forceinline__ void gemm_phase(PG8_LAS unsigned char* lds, const Gemm g, const Sched& S, const Epi& E) {
;     ...
;         for (int a = 0; a < 2; ++a)
; #pragma unroll
;             for (int b = 0; b < 2; ++b)
; #pragma unroll
;                 for (int m = 0; m < 4; ++m)
; #pragma unroll
;                     for (int n = 0; n < 2; ++n) acc[a][b][m][n] = (f32x4){0.f, 0.f, 0.f, 0.f};
.LBB0_452:
	s_add_u32 s43, s18, 0x100
	v_mov_b32_e32 v0, 0
	s_addc_u32 s45, s19, 0
	s_mov_b32 s46, -2
	s_waitcnt lgkmcnt(0)
	v_mov_b64_e32 v[0:1], 0
	v_mov_b64_e32 v[2:3], 0
	v_mov_b64_e32 v[4:5], 0
	v_mov_b64_e32 v[6:7], 0
	v_mov_b64_e32 v[16:17], 0
	v_mov_b64_e32 v[18:19], 0
	v_mov_b64_e32 v[20:21], 0
	v_mov_b64_e32 v[22:23], 0
	v_mov_b64_e32 v[32:33], 0
	v_mov_b64_e32 v[34:35], 0
	v_mov_b64_e32 v[36:37], 0
	v_mov_b64_e32 v[38:39], 0
	v_mov_b64_e32 v[48:49], 0
	v_mov_b64_e32 v[50:51], 0
	v_mov_b64_e32 v[52:53], 0
	v_mov_b64_e32 v[54:55], 0
	v_mov_b64_e32 v[8:9], 0
	v_mov_b64_e32 v[10:11], 0
	v_mov_b64_e32 v[12:13], 0
	v_mov_b64_e32 v[14:15], 0
	v_mov_b64_e32 v[24:25], 0
	v_mov_b64_e32 v[26:27], 0
	v_mov_b64_e32 v[28:29], 0
	v_mov_b64_e32 v[30:31], 0
	v_mov_b64_e32 v[40:41], 0
	v_mov_b64_e32 v[42:43], 0
	v_mov_b64_e32 v[44:45], 0
	v_mov_b64_e32 v[46:47], 0
	v_mov_b64_e32 v[56:57], 0
	v_mov_b64_e32 v[58:59], 0
	v_mov_b64_e32 v[60:61], 0
	v_mov_b64_e32 v[62:63], 0
	v_mov_b64_e32 v[64:65], 0
	v_mov_b64_e32 v[66:67], 0
	v_mov_b64_e32 v[68:69], 0
	v_mov_b64_e32 v[70:71], 0
	v_mov_b64_e32 v[80:81], 0
	v_mov_b64_e32 v[82:83], 0
	v_mov_b64_e32 v[84:85], 0
	v_mov_b64_e32 v[86:87], 0
	v_mov_b64_e32 v[96:97], 0
	v_mov_b64_e32 v[98:99], 0
	v_mov_b64_e32 v[100:101], 0
	v_mov_b64_e32 v[102:103], 0
	v_mov_b64_e32 v[112:113], 0
	v_mov_b64_e32 v[114:115], 0
	v_mov_b64_e32 v[116:117], 0
	v_mov_b64_e32 v[118:119], 0
	v_mov_b64_e32 v[72:73], 0
	v_mov_b64_e32 v[74:75], 0
	v_mov_b64_e32 v[76:77], 0
	v_mov_b64_e32 v[78:79], 0
	v_mov_b64_e32 v[88:89], 0
	v_mov_b64_e32 v[90:91], 0
	v_mov_b64_e32 v[92:93], 0
	v_mov_b64_e32 v[94:95], 0
	v_mov_b64_e32 v[104:105], 0
	v_mov_b64_e32 v[106:107], 0
	v_mov_b64_e32 v[108:109], 0
	v_mov_b64_e32 v[110:111], 0
	v_mov_b64_e32 v[120:121], 0
	v_mov_b64_e32 v[122:123], 0
	v_mov_b64_e32 v[124:125], 0
	v_mov_b64_e32 v[126:127], 0
	s_mov_b64 s[50:51], 0x80

; template <class Epi, class Sched, bool ALIGN_EPI = false, bool SP2 = false>
; __device__ __forceinline__ void gemm_phase(PG8_LAS unsigned char* lds, const Gemm g, const Sched& S, const Epi& E) {
;     ...
;         const char* nA = has_next ? (const char*)g.A + (size_t)nxt.pm * tstep + (size_t)nxt.kt0 * kstep : cA; const char* nB = has_next ? (const char*)g.Bt + (size_t)nxt.pn * tstep + (size_t)nxt.kt0 * kstep : cB;
;     ...
;         for (int a = 0; a < 2; ++a)
; #pragma unroll
;             for (int b = 0; b < 2; ++b)
; #pragma unroll
;                 for (int m = 0; m < 4; ++m)
; #pragma unroll
;                     for (int n = 0; n < 2; ++n) acc[a][b][m][n] = (f32x4){0.f, 0.f, 0.f, 0.f};
;         cur = nxt; cA = nA; cB = nB; ++ui;
.LBB0_538:
	s_ashr_i32 s13, s12, 31
	s_lshl_b64 s[14:15], s[12:13], 19
	s_add_u32 s14, s0, s14
	s_addc_u32 s15, s26, s15
	s_and_b64 s[16:17], s[8:9], exec
	s_cselect_b32 s13, s15, s23
	s_cselect_b32 s40, s14, s22
	s_ashr_i32 s11, s10, 31
	s_lshl_b64 s[16:17], s[10:11], 19
	s_add_u32 s16, s27, s16
	s_addc_u32 s17, s28, s17
	s_and_b64 s[24:25], s[8:9], exec
	s_cselect_b32 s11, s17, s21
	s_cselect_b32 s41, s16, s20
	s_add_u32 s42, s20, 0x100
	s_addc_u32 s43, s21, 0
	s_add_u32 s20, s22, 0x40080
	v_mov_b32_e32 v0, 0
	s_addc_u32 s21, s23, 0
	s_mov_b32 s45, -2
	v_mov_b64_e32 v[0:1], 0
	v_mov_b64_e32 v[2:3], 0
	v_mov_b64_e32 v[4:5], 0
	v_mov_b64_e32 v[6:7], 0
	v_mov_b64_e32 v[16:17], 0
	v_mov_b64_e32 v[18:19], 0
	v_mov_b64_e32 v[20:21], 0
	v_mov_b64_e32 v[22:23], 0
	v_mov_b64_e32 v[32:33], 0
	v_mov_b64_e32 v[34:35], 0
	v_mov_b64_e32 v[36:37], 0
	v_mov_b64_e32 v[38:39], 0
	v_mov_b64_e32 v[48:49], 0
	v_mov_b64_e32 v[50:51], 0
	v_mov_b64_e32 v[52:53], 0
	v_mov_b64_e32 v[54:55], 0
	v_mov_b64_e32 v[8:9], 0
	v_mov_b64_e32 v[10:11], 0
	v_mov_b64_e32 v[12:13], 0
	v_mov_b64_e32 v[14:15], 0
	v_mov_b64_e32 v[24:25], 0
	v_mov_b64_e32 v[26:27], 0
	v_mov_b64_e32 v[28:29], 0
	v_mov_b64_e32 v[30:31], 0
	v_mov_b64_e32 v[40:41], 0
	v_mov_b64_e32 v[42:43], 0
	v_mov_b64_e32 v[44:45], 0
	v_mov_b64_e32 v[46:47], 0
	v_mov_b64_e32 v[56:57], 0
	v_mov_b64_e32 v[58:59], 0
	v_mov_b64_e32 v[60:61], 0
	v_mov_b64_e32 v[62:63], 0
	v_mov_b64_e32 v[64:65], 0
	v_mov_b64_e32 v[66:67], 0
	v_mov_b64_e32 v[68:69], 0
	v_mov_b64_e32 v[70:71], 0
	v_mov_b64_e32 v[80:81], 0
	v_mov_b64_e32 v[82:83], 0
	v_mov_b64_e32 v[84:85], 0
	v_mov_b64_e32 v[86:87], 0
	v_mov_b64_e32 v[96:97], 0
	v_mov_b64_e32 v[98:99], 0
	v_mov_b64_e32 v[100:101], 0
	v_mov_b64_e32 v[102:103], 0
	v_mov_b64_e32 v[112:113], 0
	v_mov_b64_e32 v[114:115], 0
	v_mov_b64_e32 v[116:117], 0
	v_mov_b64_e32 v[118:119], 0
	v_mov_b64_e32 v[72:73], 0
	v_mov_b64_e32 v[74:75], 0
	v_mov_b64_e32 v[76:77], 0
	v_mov_b64_e32 v[78:79], 0
	v_mov_b64_e32 v[88:89], 0
	v_mov_b64_e32 v[90:91], 0
	v_mov_b64_e32 v[92:93], 0
	v_mov_b64_e32 v[94:95], 0
	v_mov_b64_e32 v[104:105], 0
	v_mov_b64_e32 v[106:107], 0
	v_mov_b64_e32 v[108:109], 0
	v_mov_b64_e32 v[110:111], 0
	v_mov_b64_e32 v[120:121], 0
	v_mov_b64_e32 v[122:123], 0
	v_mov_b64_e32 v[124:125], 0
	v_mov_b64_e32 v[126:127], 0
	s_mov_b64 s[50:51], 0x80

; template <bool FINAL>
; DI void gla_unit(KA a, int l, int item, LAS unsigned char* lds) {
;     ...
;         float run0 = 0.f, run1 = 0.f;
; #pragma unroll
;         for (int jj = 0; jj < 8; ++jj) {
;             const int t = 8 * tg + jj;
;             float ga = 0.f, gb = 0.f;
;             if (t < nvalid) {
;                 const u32x4* lp = (const u32x4*)(U + (size_t)(row0 + t) * UN + U_LR);
;                 float lr[16]; unpack8(lp[0], lr); unpack8(lp[1], lr + 8);
;                 float za = bg[0], zb = bg[1];
; #pragma unroll
;                 for (int e = 0; e < 16; ++e) { za += wg[0][e] * lr[e]; zb += wg[1][e] * lr[e]; }
;                 ga = (fminf(za, 0.f) - __logf(1.f + __expf(-fabsf(za)))) * (1.f / 16.f);
;                 gb = (fminf(zb, 0.f) - __logf(1.f + __expf(-fabsf(zb)))) * (1.f / 16.f);
;             }
;             run0 += ga; run1 += gb; bl[0][jj] = run0; bl[1][jj] = run1;
;         }
;         ((LAS float*)(lds + GL_GSUM))[tg * 64 + dk] = run0;
;         ((LAS float*)(lds + GL_HEAD + GL_GSUM))[tg * 64 + dk] = run1;
;     }
; #pragma unroll
;     for (int hh = 0; hh < 2; ++hh) {
;         LAS bf16_t* vT = (LAS bf16_t*)(lds + hh * GL_HEAD + GL_VT); LAS bf16_t* sT = (LAS bf16_t*)(lds + hh * GL_HEAD + GL_ST);
;         {
;             const unsigned vv[8] = {v0[hh].x, v0[hh].y, v0[hh].z, v0[hh].w, v1[hh].x, v1[hh].y, v1[hh].z, v1[hh].w};
;             const int col = ((((vj >> 3) ^ ((vdvc >> 4) & 7)) << 3) | (vj & 7));
; #pragma unroll
;             for (int e = 0; e < 8; ++e) { vT[(vdvc + 2 * e) * 72 + col] = (bf16_t)(vv[e] & 0xffffu); vT[(vdvc + 2 * e + 1) * 72 + col] = (bf16_t)(vv[e] >> 16); }
;         }
;         if (FINAL) {
; #pragma unroll
;             for (int it = 0; it < 4; ++it) {
;                 const int idx = it * 512 + tid, dkk = idx >> 5, dv4 = (idx & 31) * 4;
;                 const int col = ((((dkk >> 3) ^ ((dv4 >> 4) & 7)) << 3) | (dkk & 7));
;                 sT[(dv4 + 0) * 72 + col] = f2bf(sv[hh][it].x); sT[(dv4 + 1) * 72 + col] = f2bf(sv[hh][it].y); sT[(dv4 + 2) * 72 + col] = f2bf(sv[hh][it].z); sT[(dv4 + 3) * 72 + col] = f2bf(sv[hh][it].w);
;             }
;         }
;     }
;     LBAR();
; #pragma unroll
;     for (int hh = 0; hh < 2; ++hh) {
;         LAS float* gsum = (LAS float*)(lds + hh * GL_HEAD + GL_GSUM); LAS float* dS = (LAS float*)(lds + hh * GL_HEAD + GL_DS);
.LBB0_665:
	v_mov_b32_e32 v16, v43
	s_waitcnt vmcnt(24)
	v_pk_add_f32 v[30:31], v[20:21], v[16:17]
	v_mov_b32_e32 v16, v21
	s_waitcnt vmcnt(20)
	v_pk_add_f32 v[24:25], v[16:17], v[42:43]
	v_mov_b32_e32 v16, v47
	s_waitcnt vmcnt(1)
	v_pk_add_f32 v[28:29], v[24:25], v[46:47]
	v_pk_add_f32 v[32:33], v[30:31], v[16:17]
	v_mov_b32_e32 v16, v45
	v_pk_add_f32 v[26:27], v[28:29], v[44:45]
	v_pk_add_f32 v[34:35], v[32:33], v[16:17]
	v_pk_add_f32 v[22:23], v[26:27], v[50:51]
	s_and_b32 s0, s48, 0x3fffffc0
	v_pk_add_f32 v[18:19], v[22:23], v[48:49]
	v_add_f32_e32 v23, v34, v51
	v_add_f32_e32 v25, v23, v49
	v_add_f32_e32 v27, v25, v55
	v_or_b32_e32 v29, s0, v75
	v_pk_add_f32 v[16:17], v[18:19], v[54:55]
	v_add_f32_e32 v19, v27, v53
	v_lshl_add_u32 v29, v29, 2, 0
	v_add_f32_e32 v17, v16, v52
	ds_write_b32 v29, v19
	v_add_u32_e32 v29, 0x10c00, v29
	ds_write_b32 v29, v17
	v_ashrrev_i32_e32 v29, 6, v107
	v_lshrrev_b32_e32 v33, 2, v107
	v_bitop3_b32 v29, v29, v107, 7 bitop3:0x78
	v_and_b32_e32 v33, 14, v33
	v_mul_u32_u24_e32 v31, 0x90, v108
	v_lshl_or_b32 v29, v29, 4, v33
	v_add3_u32 v31, 0, v31, v29
	v_readlane_b32 s4, v254, 47
	ds_write_b16 v31, v4 offset:22528
	ds_write_b16_d16_hi v31, v4 offset:22672
	s_movk_i32 s0, 0x90
	ds_write_b16 v31, v5 offset:22816
	ds_write_b16_d16_hi v31, v5 offset:22960
	ds_write_b16 v31, v6 offset:23104
	ds_write_b16_d16_hi v31, v6 offset:23248
	ds_write_b16 v31, v7 offset:23392
	ds_write_b16_d16_hi v31, v7 offset:23536
	ds_write_b16 v31, v0 offset:23680
	ds_write_b16_d16_hi v31, v0 offset:23824
	ds_write_b16 v31, v1 offset:23968
	ds_write_b16_d16_hi v31, v1 offset:24112
	ds_write_b16 v31, v2 offset:24256
	ds_write_b16_d16_hi v31, v2 offset:24400
	ds_write_b16 v31, v3 offset:24544
	ds_write_b16_d16_hi v31, v3 offset:24688
	v_add_u32_e32 v3, s4, v29
	v_mad_u32_u24 v4, v108, s0, v223
	v_mad_u32_u24 v31, v108, s0, v3
	v_mad_u32_u24 v5, v108, s0, v224
	ds_write_b16 v31, v12
	ds_write_b16_d16_hi v31, v12 offset:144
	v_add_u32_e32 v12, v3, v4
	v_add3_u32 v4, s4, v4, v29
	ds_write_b16_d16_hi v4, v13 offset:144
	v_add_u32_e32 v4, v3, v5
	v_mad_u32_u24 v6, v108, s0, v225
	ds_write_b16 v4, v14
	v_add3_u32 v4, s4, v5, v29
	ds_write_b16_d16_hi v4, v14 offset:144
	v_add_u32_e32 v4, v3, v6
	v_mad_u32_u24 v7, v108, s0, v226
	ds_write_b16 v4, v15
	v_add3_u32 v4, s4, v6, v29
	ds_write_b16_d16_hi v4, v15 offset:144
	v_add_u32_e32 v4, v3, v7
	v_mad_u32_u24 v0, v108, s0, v227
	ds_write_b16 v4, v8
	v_add3_u32 v4, s4, v7, v29
	v_mad_u32_u24 v1, v108, s0, v228
	ds_write_b16_d16_hi v4, v8 offset:144
	v_add_u32_e32 v4, v3, v0
	v_add3_u32 v0, s4, v0, v29
	ds_write_b16_d16_hi v0, v9 offset:144
	v_add_u32_e32 v0, v3, v1
	v_mad_u32_u24 v2, v108, s0, v229
	ds_write_b16 v0, v10
	v_add3_u32 v0, s4, v1, v29
	ds_write_b16_d16_hi v0, v10 offset:144
	v_add_u32_e32 v0, v3, v2
	ds_write_b16 v0, v11
	v_add3_u32 v0, s4, v2, v29
	ds_write_b16 v12, v13
	ds_write_b16 v4, v9
	ds_write_b16_d16_hi v0, v11 offset:144
	s_waitcnt lgkmcnt(0)
	s_barrier
	v_add_u32_e32 v10, 0, v144
	s_lshl_b32 s0, s47, 4
	ds_read2st64_b32 v[2:3], v10 offset1:1
	s_cmp_lt_u32 s48, 64
	s_cselect_b64 s[6:7], -1, 0
	s_lshl_b32 s26, s50, 2
	s_or_b32 s4, s26, s49
	s_cmp_gt_i32 s47, 0
	s_waitcnt lgkmcnt(0)
	v_add_f32_e32 v2, 0, v2
	s_cselect_b64 s[22:23], -1, 0
	ds_read2st64_b32 v[4:5], v10 offset0:2 offset1:3
	ds_read2st64_b32 v[6:7], v10 offset0:4 offset1:5
	ds_read2st64_b32 v[8:9], v10 offset0:6 offset1:7
	s_cmp_gt_i32 s47, 1
	v_cndmask_b32_e64 v0, 0, v2, s[22:23]
	v_add_f32_e32 v1, v3, v0
	s_cselect_b64 s[24:25], -1, 0
	s_cmp_gt_i32 s47, 2
	v_cndmask_b32_e64 v0, v0, v1, s[24:25]
	s_waitcnt lgkmcnt(2)
	v_add_f32_e32 v1, v4, v0
	s_cselect_b64 s[18:19], -1, 0
	s_cmp_gt_i32 s47, 3
	v_cndmask_b32_e64 v0, v0, v1, s[18:19]
	v_add_f32_e32 v1, v5, v0
	s_cselect_b64 s[20:21], -1, 0
	s_cmp_gt_i32 s47, 4
	v_cndmask_b32_e64 v0, v0, v1, s[20:21]
	s_waitcnt lgkmcnt(1)
	v_add_f32_e32 v1, v6, v0
	s_cselect_b64 s[14:15], -1, 0
	s_cmp_gt_i32 s47, 5
	v_cndmask_b32_e64 v0, v0, v1, s[14:15]
	v_add_f32_e32 v1, v7, v0
	s_cselect_b64 s[16:17], -1, 0
	v_add_f32_e32 v2, v2, v3
	s_cmp_gt_i32 s47, 6
	v_cndmask_b32_e64 v0, v0, v1, s[16:17]
	v_add_f32_e32 v2, v2, v4
	s_waitcnt lgkmcnt(0)
	v_add_f32_e32 v1, v8, v0
	s_cselect_b64 s[10:11], -1, 0
	v_add_f32_e32 v2, v2, v5
	s_cmp_gt_i32 s47, 7
	v_cndmask_b32_e64 v11, v0, v1, s[10:11]
	v_add_f32_e32 v2, v2, v6
	v_add_f32_e32 v12, v9, v11
	s_cselect_b64 s[12:13], -1, 0
	v_add_f32_e32 v2, v2, v7
	v_add_f32_e32 v2, v2, v8
	v_cndmask_b32_e64 v7, v11, v12, s[12:13]
	s_cmpk_gt_i32 s50, 0x107
	s_cbranch_scc1 .Lm1b0_samp
	s_mul_hi_i32 s72, s50, 0x3e0f83e1
	s_lshr_b32 s73, s72, 31
	s_ashr_i32 s72, s72, 3
	s_add_i32 s72, s72, s73
	s_mul_i32 s72, s72, 0xffffffdf
	s_add_i32 s72, s72, s50
	s_cmp_eq_u32 s72, 0
	s_cselect_b32 s72, 16, 64
	s_branch .Lm1b0_go
; DI float bf2f(unsigned v) { return __uint_as_float(v << 16); }
; DI bf16_t f2bf(float f) { return (bf16_t)(cvt_pk(f, 0.f) & 0xffffu); }
; template <bool FINAL>
; DI void gla_unit(KA a, int l, int item, LAS unsigned char* lds) {
;     ...
;         for (int jj = 0; jj < 8; ++jj) {
;             const int t = 8 * tg + jj;
;             const float bj = prefix + bl[hh][jj];
;             const float kv = bf2f(kraw[hh][jj]);
;             if (FINAL) { qs[t * 72 + dk] = f2bf(bf2f(qraw[hh][jj]) * 0.125f * __expf(bj)); ks[t * 72 + dk] = f2bf(kv * __expf(-bj)); }
;             else ks[dk * 72 + t] = f2bf(kv * __expf(blast - bj));
;         }
;         if (!FINAL && tg == 0) { const float d = __expf(blast); dS[dk] = d; if (u.prompt) ((float*)(a->ws + WS_DBUF))[(size_t)(unit * 4 + 2 * hp + hh) * 64 + dk] = d; }
.Lm1b0_samp:
	s_mov_b32 s72, 8
.Lm1b0_go:
	s_cmp_lt_i32 s59, s72
	s_cbranch_scc0 .Lm1b0_skip
	s_add_i32 s72, s59, s51
	s_lshl_b32 s72, s72, 11
	s_lshl_b32 s73, s49, 8
	s_add_i32 s72, s72, s73
	s_add_u32 s72, s28, s72
	s_addc_u32 s73, s29, 0
	s_add_u32 s72, s72, 0xaf00400
	s_addc_u32 s73, s73, 0
	s_add_u32 s74, s72, 0x1000
	s_addc_u32 s75, s73, 0
	s_add_u32 s76, s72, 0x2000
	s_addc_u32 s77, s73, 0
	s_add_u32 s78, s72, 0x3000
	s_addc_u32 s79, s73, 0
	v_lshlrev_b32_e32 v128, 2, v75
	v_add_f32_e32 v109, v20, v7
	v_add_f32_e32 v110, v30, v7
	v_add_f32_e32 v111, v32, v7
	v_add_f32_e32 v112, v34, v7
	v_add_f32_e32 v113, v23, v7
	v_add_f32_e32 v114, v25, v7
	v_add_f32_e32 v115, v27, v7
	v_add_f32_e32 v116, v19, v7
	global_store_dword v128, v109, s[72:73]
	global_store_dword v128, v110, s[72:73] offset:2048
	global_store_dword v128, v111, s[74:75]
	global_store_dword v128, v112, s[74:75] offset:2048
	global_store_dword v128, v113, s[76:77]
	global_store_dword v128, v114, s[76:77] offset:2048
	global_store_dword v128, v115, s[78:79]
	global_store_dword v128, v116, s[78:79] offset:2048
.Lm1b0_skip:
	s_movk_i32 s5, 0x8c
	v_mov_b32_e32 v3, v34
	v_mov_b32_e32 v6, v9
	v_mad_u32_u24 v4, v75, s5, v10
	v_add_f32_e32 v8, v20, v7
	v_add_f32_e32 v10, v30, v7
	v_pk_add_f32 v[2:3], v[2:3], v[6:7]
	v_add_f32_e32 v9, v32, v7
	v_sub_f32_e32 v6, v2, v8
	v_sub_f32_e32 v8, v2, v10
	v_sub_f32_e32 v9, v2, v9
	v_sub_f32_e32 v3, v2, v3
	v_mul_f32_e32 v6, 0x3fb8aa3b, v6
	v_mul_f32_e32 v8, 0x3fb8aa3b, v8
	v_mul_f32_e32 v9, 0x3fb8aa3b, v9
	v_mul_f32_e32 v3, 0x3fb8aa3b, v3
	v_add_f32_e32 v10, v25, v7
	v_exp_f32_e32 v6, v6
	v_exp_f32_e32 v8, v8
	v_exp_f32_e32 v9, v9
	v_exp_f32_e32 v3, v3
	v_sub_f32_e32 v10, v2, v10
	v_mul_f32_e32 v10, 0x3fb8aa3b, v10
	v_exp_f32_e32 v10, v10
	v_mul_f32_e32 v6, v93, v6
	v_mul_f32_e32 v8, v90, v8
	v_mul_f32_e32 v9, v100, v9
	v_mul_f32_e32 v3, v99, v3
	v_cvt_pk_bf16_f32 v6, v6, v145
	v_cvt_pk_bf16_f32 v8, v8, v145
	v_cvt_pk_bf16_f32 v9, v9, v145
	v_cvt_pk_bf16_f32 v3, v3, v145
	s_mov_b32 s5, 0x5040100
	v_perm_b32 v9, v3, v9, s5
	v_add_f32_e32 v3, v23, v7
	v_perm_b32 v8, v8, v6, s5
	v_mul_f32_e32 v6, v102, v10
	v_add_f32_e32 v10, v27, v7
	v_add_f32_e32 v7, v19, v7
	v_sub_f32_e32 v3, v2, v3
	v_sub_f32_e32 v7, v2, v7
	v_mul_f32_e32 v3, 0x3fb8aa3b, v3
	v_sub_f32_e32 v10, v2, v10
	v_mul_f32_e32 v7, 0x3fb8aa3b, v7
	v_exp_f32_e32 v3, v3
	v_mul_f32_e32 v10, 0x3fb8aa3b, v10
	v_exp_f32_e32 v7, v7
	v_exp_f32_e32 v10, v10
	v_mul_f32_e32 v3, v104, v3
	v_add_u32_e32 v5, s0, v4
	v_mul_f32_e32 v7, v105, v7
	v_cvt_pk_bf16_f32 v3, v3, v145
	v_cvt_pk_bf16_f32 v6, v6, v145
	v_mul_f32_e32 v10, v106, v10
	v_cvt_pk_bf16_f32 v7, v7, v145
	v_cvt_pk_bf16_f32 v10, v10, v145
	v_perm_b32 v6, v6, v3, s5
	v_perm_b32 v7, v7, v10, s5
	v_add_u32_e32 v3, 0x3000, v5
	v_lshl_add_u64 v[0:1], s[28:29], 0, v[144:145]
	s_mov_b64 s[8:9], 0x380000
	ds_write2_b64 v3, v[8:9], v[6:7] offset0:128 offset1:129
	v_cndmask_b32_e64 v3, 0, 1, s[30:31]
	s_movk_i32 s27, 0x90
	s_cmp_gt_u32 s48, 63
	v_lshl_add_u64 v[0:1], v[0:1], 0, s[8:9]
	v_cmp_ne_u32_e64 s[8:9], 1, v3
	s_cbranch_scc1 .LBB0_668
	v_mul_f32_e32 v2, 0x3fb8aa3b, v2
	v_exp_f32_e32 v2, v2
	s_movk_i32 s5, 0xff74
	v_mad_i32_i24 v3, v75, s5, v4
	s_and_b64 vcc, exec, s[8:9]
	ds_write_b32 v3, v2 offset:2048
	s_cbranch_vccnz .LBB0_668
	s_ashr_i32 s5, s4, 31
	s_lshl_b64 s[30:31], s[4:5], 8
	v_lshl_add_u64 v[4:5], v[0:1], 0, s[30:31]
	global_store_dword v[4:5], v2, off
.LBB0_668:
	v_lshl_add_u32 v4, v75, 2, 0
	v_add_u32_e32 v5, 0x10c00, v4
	ds_read2st64_b32 v[2:3], v5 offset1:1
	s_add_i32 s0, s0, 0
	s_andn2_b64 vcc, exec, s[6:7]
	s_waitcnt lgkmcnt(0)
	v_add_f32_e32 v2, 0, v2
	v_cndmask_b32_e64 v6, 0, v2, s[22:23]
	v_add_f32_e32 v7, v2, v3
	v_add_f32_e32 v2, v3, v6
	v_cndmask_b32_e64 v6, v6, v2, s[24:25]
	ds_read2st64_b32 v[2:3], v5 offset0:2 offset1:3
	s_waitcnt lgkmcnt(0)
	v_add_f32_e32 v7, v7, v2
	v_add_f32_e32 v2, v2, v6
	v_cndmask_b32_e64 v2, v6, v2, s[18:19]
	v_add_f32_e32 v6, v7, v3
	v_add_f32_e32 v3, v3, v2
	v_cndmask_b32_e64 v7, v2, v3, s[20:21]
	ds_read2st64_b32 v[2:3], v5 offset0:4 offset1:5
	s_waitcnt lgkmcnt(0)
	v_add_f32_e32 v6, v6, v2
	v_add_f32_e32 v2, v2, v7
	v_cndmask_b32_e64 v2, v7, v2, s[14:15]
	v_add_f32_e32 v6, v6, v3
	v_add_f32_e32 v3, v3, v2
	v_cndmask_b32_e64 v7, v2, v3, s[16:17]
	ds_read2st64_b32 v[2:3], v5 offset0:6 offset1:7
	s_waitcnt lgkmcnt(0)
	v_add_f32_e32 v6, v6, v2
	v_add_f32_e32 v2, v2, v7
	v_cndmask_b32_e64 v2, v7, v2, s[10:11]
	v_add_f32_e32 v5, v3, v2
	v_cndmask_b32_e64 v9, v2, v5, s[12:13]
	s_cmpk_gt_i32 s50, 0x107
	s_cbranch_scc1 .Lm1b1_samp
	s_mul_hi_i32 s72, s50, 0x3e0f83e1
	s_lshr_b32 s73, s72, 31
	s_ashr_i32 s72, s72, 3
	s_add_i32 s72, s72, s73
	s_mul_i32 s72, s72, 0xffffffdf
	s_add_i32 s72, s72, s50
	s_cmp_eq_u32 s72, 0
	s_cselect_b32 s72, 16, 64
	s_branch .Lm1b1_go

; DI float bf2f(unsigned v) { return __uint_as_float(v << 16); }
; DI bf16_t f2bf(float f) { return (bf16_t)(cvt_pk(f, 0.f) & 0xffffu); }
; template <bool FINAL>
; DI void gla_unit(KA a, int l, int item, LAS unsigned char* lds) {
;     ...
;         for (int jj = 0; jj < 8; ++jj) {
;             const int t = 8 * tg + jj;
;             const float bj = prefix + bl[hh][jj];
;             const float kv = bf2f(kraw[hh][jj]);
;             if (FINAL) { qs[t * 72 + dk] = f2bf(bf2f(qraw[hh][jj]) * 0.125f * __expf(bj)); ks[t * 72 + dk] = f2bf(kv * __expf(-bj)); }
;             else ks[dk * 72 + t] = f2bf(kv * __expf(blast - bj));
;         }
;         if (!FINAL && tg == 0) { const float d = __expf(blast); dS[dk] = d; if (u.prompt) ((float*)(a->ws + WS_DBUF))[(size_t)(unit * 4 + 2 * hp + hh) * 64 + dk] = d; }
.Lm1b1_go:
	s_cmp_lt_i32 s59, s72
	s_cbranch_scc0 .Lm1b1_skip
	s_add_i32 s72, s59, s51
	s_lshl_b32 s72, s72, 11
	s_lshl_b32 s73, s49, 8
	s_add_i32 s72, s72, s73
	s_add_u32 s72, s28, s72
	s_addc_u32 s73, s29, 0
	s_add_u32 s72, s72, 0xaf00500
	s_addc_u32 s73, s73, 0
	s_add_u32 s74, s72, 0x1000
	s_addc_u32 s75, s73, 0
	s_add_u32 s76, s72, 0x2000
	s_addc_u32 s77, s73, 0
	s_add_u32 s78, s72, 0x3000
	s_addc_u32 s79, s73, 0
	v_lshlrev_b32_e32 v128, 2, v75
	v_add_f32_e32 v117, v21, v9
	v_add_f32_e32 v118, v24, v9
	v_add_f32_e32 v119, v28, v9
	v_add_f32_e32 v120, v26, v9
	v_add_f32_e32 v121, v22, v9
	v_add_f32_e32 v122, v18, v9
	v_add_f32_e32 v129, v16, v9
	v_add_f32_e32 v109, v17, v9
	global_store_dword v128, v117, s[72:73]
	global_store_dword v128, v118, s[72:73] offset:2048
	global_store_dword v128, v119, s[74:75]
	global_store_dword v128, v120, s[74:75] offset:2048
	global_store_dword v128, v121, s[76:77]
	global_store_dword v128, v122, s[76:77] offset:2048
	global_store_dword v128, v129, s[78:79]
	global_store_dword v128, v109, s[78:79] offset:2048
.Lm1b1_skip:
	v_mov_b32_e32 v2, s0
	v_mad_u32_u24 v2, v75, s27, v2
	v_mov_b32_e32 v7, v26
	v_mov_b32_e32 v8, v3
	v_add_u32_e32 v5, 0x14000, v2
	v_add_f32_e32 v11, v24, v9
	v_pk_add_f32 v[2:3], v[6:7], v[8:9]
	v_add_f32_e32 v10, v21, v9
	v_sub_f32_e32 v7, v2, v11
	v_mul_f32_e32 v7, 0x3fb8aa3b, v7
	v_exp_f32_e32 v7, v7
	v_add_f32_e32 v12, v28, v9
	v_sub_f32_e32 v6, v2, v10
	v_sub_f32_e32 v3, v2, v3
	v_mul_f32_e32 v7, v89, v7
	v_cvt_pk_bf16_f32 v8, v7, v145
	v_sub_f32_e32 v7, v2, v12
	v_mul_f32_e32 v6, 0x3fb8aa3b, v6
	v_mul_f32_e32 v7, 0x3fb8aa3b, v7
	v_mul_f32_e32 v3, 0x3fb8aa3b, v3
	v_exp_f32_e32 v6, v6
	v_exp_f32_e32 v7, v7
	v_exp_f32_e32 v3, v3
	s_mov_b32 s0, 0x5040100
	v_mul_f32_e32 v6, v95, v6
	v_mul_f32_e32 v7, v97, v7
	v_mul_f32_e32 v3, v91, v3
	v_cvt_pk_bf16_f32 v6, v6, v145
	v_cvt_pk_bf16_f32 v7, v7, v145
	v_cvt_pk_bf16_f32 v3, v3, v145
	v_add_f32_e32 v10, v16, v9
	v_perm_b32 v7, v3, v7, s0
	v_perm_b32 v6, v8, v6, s0
	v_add_f32_e32 v3, v22, v9
	v_add_f32_e32 v8, v18, v9
	v_add_f32_e32 v9, v17, v9
	v_sub_f32_e32 v8, v2, v8
	v_sub_f32_e32 v9, v2, v9
	v_sub_f32_e32 v3, v2, v3
	v_mul_f32_e32 v8, 0x3fb8aa3b, v8
	v_sub_f32_e32 v10, v2, v10
	v_mul_f32_e32 v9, 0x3fb8aa3b, v9
	v_mul_f32_e32 v3, 0x3fb8aa3b, v3
	v_exp_f32_e32 v8, v8
	v_mul_f32_e32 v10, 0x3fb8aa3b, v10
	v_exp_f32_e32 v9, v9
	v_exp_f32_e32 v3, v3
	v_exp_f32_e32 v10, v10
	v_mul_f32_e32 v8, v92, v8
	v_mul_f32_e32 v9, v94, v9
	v_mul_f32_e32 v3, v98, v3
	v_cvt_pk_bf16_f32 v8, v8, v145
	v_mul_f32_e32 v10, v101, v10
	v_cvt_pk_bf16_f32 v9, v9, v145
	v_cvt_pk_bf16_f32 v3, v3, v145
	v_cvt_pk_bf16_f32 v10, v10, v145
	s_nop 0
	v_perm_b32 v9, v9, v10, s0
	v_perm_b32 v8, v8, v3, s0
	ds_write2_b64 v5, v[6:7], v[8:9] offset1:1
	s_cbranch_vccnz .LBB0_671
	v_mul_f32_e32 v2, 0x3fb8aa3b, v2
	v_exp_f32_e32 v2, v2
	v_add_u32_e32 v3, 0x11400, v4
	s_and_b64 vcc, exec, s[8:9]
	ds_write_b32 v3, v2
	s_cbranch_vccnz .LBB0_671
	s_or_b32 s6, s4, 1
	s_ashr_i32 s7, s6, 31
	s_lshl_b64 s[6:7], s[6:7], 8
	v_lshl_add_u64 v[0:1], v[0:1], 0, s[6:7]
	global_store_dword v[0:1], v2, off

; #define LAS __attribute__((address_space(3)))
; DI int crow(int reg, int h) { return (reg & 3) + 8 * (reg >> 2) + 4 * h; }
; template <bool FINAL>
; DI void gla_unit(KA a, int l, int item, LAS unsigned char* lds) {
;     ...
;     if (FINAL) {
; #pragma unroll
;         for (int q = 0; q < 4; ++q) gnv[q] = *(const f32x4*)(a->in[20] + l * DV + vdvc + 4 * q);
;     }
;     float s0v[2][16];
;     if (!FINAL && !u.prompt) {
; #pragma unroll
;         for (int hh = 0; hh < 2; ++hh)
; #pragma unroll
;             for (int i = 0; i < 16; ++i) s0v[hh][i] = __builtin_nontemporal_load(S0[hh] + (32 * (w >> 2) + crow(i, h)) * 128 + 32 * (w & 3) + r);
;     }
;     float bl[2][8];
;     {
;         float wg[2][16], bg[2];
; #pragma unroll
;         for (int hh = 0; hh < 2; ++hh) {
;             const float* wg2 = a->in[18] + (size_t)l * 16 * 256 + (2 * hp + hh) * 64 + dk;
; #pragma unroll
;             for (int e = 0; e < 16; ++e) wg[hh][e] = wg2[e * 256];
;             bg[hh] = a->in[19][l * 256 + (2 * hp + hh) * 64 + dk];
;         }
;         float run0 = 0.f, run1 = 0.f;
; #pragma unroll
;         for (int jj = 0; jj < 8; ++jj) {
;             const int t = 8 * tg + jj;
;             float ga = 0.f, gb = 0.f;
;             if (t < nvalid) {
;                 const u32x4* lp = (const u32x4*)(U + (size_t)(row0 + t) * UN + U_LR);
;                 float lr[16]; unpack8(lp[0], lr); unpack8(lp[1], lr + 8);
;                 float za = bg[0], zb = bg[1];
; #pragma unroll
;                 for (int e = 0; e < 16; ++e) { za += wg[0][e] * lr[e]; zb += wg[1][e] * lr[e]; }
;                 ga = (fminf(za, 0.f) - __logf(1.f + __expf(-fabsf(za)))) * (1.f / 16.f);
;                 gb = (fminf(zb, 0.f) - __logf(1.f + __expf(-fabsf(zb)))) * (1.f / 16.f);
;             }
;             run0 += ga; run1 += gb; bl[0][jj] = run0; bl[1][jj] = run1;
;         }
;         ((LAS float*)(lds + GL_GSUM))[tg * 64 + dk] = run0;
;         ((LAS float*)(lds + GL_HEAD + GL_GSUM))[tg * 64 + dk] = run1;
;     }
.LBB0_885:
	s_load_dwordx2 s[2:3], s[2:3], 0xa0
	s_lshl_b64 s[26:27], s[60:61], 2
	v_lshlrev_b32_e32 v124, 2, v167
	s_waitcnt lgkmcnt(0)
	s_add_u32 s2, s2, s26
	s_addc_u32 s3, s3, s27
	global_load_dwordx4 v[32:35], v124, s[2:3] offset:48
	global_load_dwordx4 v[52:55], v124, s[2:3] offset:32
	global_load_dwordx4 v[56:59], v124, s[2:3] offset:16
	global_load_dwordx4 v[60:63], v124, s[2:3]
	v_mov_b32_e32 v86, 0
	v_mov_b32_e32 v106, 0
	v_mov_b32_e32 v104, 0
	v_mov_b32_e32 v102, 0
	v_mov_b32_e32 v100, 0
	v_mov_b32_e32 v98, 0
	v_mov_b32_e32 v96, 0
	v_mov_b32_e32 v83, 0
	v_mov_b32_e32 v87, 0
	v_mov_b32_e32 v94, 0
	v_mov_b32_e32 v92, 0
	v_mov_b32_e32 v90, 0
	v_mov_b32_e32 v88, 0
	v_mov_b32_e32 v82, 0
	v_mov_b32_e32 v80, 0
	v_mov_b32_e32 v81, 0
	s_and_b64 vcc, exec, s[24:25]
	s_cbranch_vccnz .Lm3_bl_skip
	s_add_i32 s72, s53, s46
	s_lshl_b32 s72, s72, 11
	s_lshl_b32 s73, s54, 2
	s_add_i32 s72, s72, s73
	s_add_u32 s72, s30, s72
	s_addc_u32 s73, s31, 0
	s_add_u32 s72, s72, 0x5f00400
	s_addc_u32 s73, s73, 0
	s_add_u32 s74, s72, 0x1000
	s_addc_u32 s75, s73, 0
	s_add_u32 s76, s72, 0x2000
	s_addc_u32 s77, s73, 0
	s_add_u32 s78, s72, 0x3000
	s_addc_u32 s79, s73, 0
	v_lshlrev_b32_e32 v108, 2, v85
	global_load_dword v86, v108, s[72:73]
	global_load_dword v87, v108, s[72:73] offset:256
	global_load_dword v106, v108, s[72:73] offset:2048
	global_load_dword v94, v108, s[72:73] offset:2304
	global_load_dword v104, v108, s[74:75]
	global_load_dword v92, v108, s[74:75] offset:256
	global_load_dword v102, v108, s[74:75] offset:2048
	global_load_dword v90, v108, s[74:75] offset:2304
	global_load_dword v100, v108, s[76:77]
	global_load_dword v88, v108, s[76:77] offset:256
	global_load_dword v98, v108, s[76:77] offset:2048
	global_load_dword v82, v108, s[76:77] offset:2304
	global_load_dword v96, v108, s[78:79]
	global_load_dword v80, v108, s[78:79] offset:256
	global_load_dword v83, v108, s[78:79] offset:2048
	global_load_dword v81, v108, s[78:79] offset:2304
.Lm3_bl_skip:
.LBB0_901:
	s_waitcnt vmcnt(0)
	v_mul_f32_e32 v140, 0x3e000000, v140
	v_mul_f32_e32 v136, 0x3e000000, v136
	v_mul_f32_e32 v138, 0x3e000000, v138
	v_mul_f32_e32 v132, 0x3e000000, v132
	v_mul_f32_e32 v135, 0x3e000000, v135
	v_mul_f32_e32 v128, 0x3e000000, v128
	v_mul_f32_e32 v131, 0x3e000000, v131
	v_mul_f32_e32 v125, 0x3e000000, v125
	v_mul_f32_e32 v154, 0x3e000000, v154
	v_mul_f32_e32 v141, 0x3e000000, v141
	v_mul_f32_e32 v157, 0x3e000000, v157
	v_mul_f32_e32 v143, 0x3e000000, v143
	v_mul_f32_e32 v161, 0x3e000000, v161
	v_mul_f32_e32 v159, 0x3e000000, v159
	v_mul_f32_e32 v165, 0x3e000000, v165
	v_mul_f32_e32 v163, 0x3e000000, v163
	s_andn2_b64 vcc, exec, s[66:67]
	s_cbranch_vccnz .Lm3_nu0
	v_lshlrev_b32_e32 v8, 16, v10
	v_and_b32_e32 v9, 0xffff0000, v10
	v_lshlrev_b32_e32 v10, 16, v11
	v_and_b32_e32 v11, 0xffff0000, v11
	v_lshlrev_b32_e32 v12, 16, v14
	v_and_b32_e32 v13, 0xffff0000, v14
	v_lshlrev_b32_e32 v14, 16, v15
	v_and_b32_e32 v15, 0xffff0000, v15
	v_lshlrev_b32_e32 v16, 16, v18
	v_and_b32_e32 v17, 0xffff0000, v18
	v_lshlrev_b32_e32 v18, 16, v19
	v_and_b32_e32 v19, 0xffff0000, v19
	v_lshlrev_b32_e32 v20, 16, v22
	v_and_b32_e32 v21, 0xffff0000, v22
	v_lshlrev_b32_e32 v22, 16, v23
	v_and_b32_e32 v23, 0xffff0000, v23

; #define LAS __attribute__((address_space(3)))
; DI bf16_t f2bf(float f) { return (bf16_t)(cvt_pk(f, 0.f) & 0xffffu); }
; #define LBAR() do { asm volatile("s_waitcnt lgkmcnt(0)" ::: "memory"); __builtin_amdgcn_s_barrier(); asm volatile("" ::: "memory"); } while (0)
; template <bool FINAL>
; DI void gla_unit(KA a, int l, int item, LAS unsigned char* lds) {
;     ...
; #pragma unroll
;     for (int hh = 0; hh < 2; ++hh) {
;         LAS bf16_t* vT = (LAS bf16_t*)(lds + hh * GL_HEAD + GL_VT); LAS bf16_t* sT = (LAS bf16_t*)(lds + hh * GL_HEAD + GL_ST);
;         {
;             const unsigned vv[8] = {v0[hh].x, v0[hh].y, v0[hh].z, v0[hh].w, v1[hh].x, v1[hh].y, v1[hh].z, v1[hh].w};
;             const int col = ((((vj >> 3) ^ ((vdvc >> 4) & 7)) << 3) | (vj & 7));
; #pragma unroll
;             for (int e = 0; e < 8; ++e) { vT[(vdvc + 2 * e) * 72 + col] = (bf16_t)(vv[e] & 0xffffu); vT[(vdvc + 2 * e + 1) * 72 + col] = (bf16_t)(vv[e] >> 16); }
;         }
;         if (FINAL) {
; #pragma unroll
;             for (int it = 0; it < 4; ++it) {
;                 const int idx = it * 512 + tid, dkk = idx >> 5, dv4 = (idx & 31) * 4;
;                 const int col = ((((dkk >> 3) ^ ((dv4 >> 4) & 7)) << 3) | (dkk & 7));
;                 sT[(dv4 + 0) * 72 + col] = f2bf(sv[hh][it].x); sT[(dv4 + 1) * 72 + col] = f2bf(sv[hh][it].y); sT[(dv4 + 2) * 72 + col] = f2bf(sv[hh][it].z); sT[(dv4 + 3) * 72 + col] = f2bf(sv[hh][it].w);
;             }
;         }
;     }
;     LBAR();
; #pragma unroll
;     for (int hh = 0; hh < 2; ++hh) {
;         LAS float* gsum = (LAS float*)(lds + hh * GL_HEAD + GL_GSUM); LAS float* dS = (LAS float*)(lds + hh * GL_HEAD + GL_DS);
;         LAS bf16_t* qs = (LAS bf16_t*)(lds + hh * GL_HEAD + GL_QS); LAS bf16_t* ks = (LAS bf16_t*)(lds + hh * GL_HEAD + GL_KS);
;         float prefix = 0.f, blast = 0.f;
; #pragma unroll
;         for (int g2 = 0; g2 < 8; ++g2) { const float v = gsum[g2 * 64 + dk]; blast += v; if (g2 < tg) prefix += v; }
.Lm3_nu1:
	v_ashrrev_i32_e32 v89, 6, v123
	v_lshrrev_b32_e32 v97, 2, v123
	v_bitop3_b32 v89, v89, v123, 7 bitop3:0x78
	v_and_b32_e32 v97, 14, v97
	v_mul_u32_u24_e32 v95, 0x90, v167
	v_lshl_or_b32 v89, v89, 4, v97
	v_add3_u32 v95, 0, v95, v89
	v_lshrrev_b32_e32 v91, 4, v169
	v_ashrrev_i32_e32 v93, 8, v123
	ds_write_b16 v95, v4 offset:22528
	ds_write_b16_d16_hi v95, v4 offset:22672
	ds_write_b16 v95, v5 offset:22816
	ds_write_b16_d16_hi v95, v5 offset:22960
	ds_write_b16 v95, v6 offset:23104
	ds_write_b16_d16_hi v95, v6 offset:23248
	ds_write_b16 v95, v7 offset:23392
	ds_write_b16_d16_hi v95, v7 offset:23536
	ds_write_b16 v95, v0 offset:23680
	ds_write_b16_d16_hi v95, v0 offset:23824
	ds_write_b16 v95, v1 offset:23968
	ds_write_b16_d16_hi v95, v1 offset:24112
	ds_write_b16 v95, v2 offset:24256
	ds_write_b16_d16_hi v95, v2 offset:24400
	ds_write_b16 v95, v3 offset:24544
	ds_write_b16_d16_hi v95, v3 offset:24688
	v_lshrrev_b32_e32 v95, 4, v123
	v_bitop3_b32 v93, v91, v93, 7 bitop3:0x6c
	s_movk_i32 s0, 0x90
	v_and_b32_e32 v95, 14, v95
	v_mad_u32_u24 v3, v168, s0, 0
	v_lshl_or_b32 v93, v93, 4, v95
	v_cvt_pk_bf16_f32 v8, v8, v145
	v_add_u32_e32 v97, v3, v93
	ds_write_b16 v97, v8 offset:40960
	v_cvt_pk_bf16_f32 v8, v9, v145
	ds_write_b16 v97, v8 offset:41104
	v_cvt_pk_bf16_f32 v8, v10, v145
	ds_write_b16 v97, v8 offset:41248
	v_cvt_pk_bf16_f32 v8, v11, v145
	ds_write_b16 v97, v8 offset:41392
	v_ashrrev_i32_e32 v8, 8, v170
	v_bitop3_b32 v8, v91, v8, 7 bitop3:0x6c
	v_lshl_or_b32 v8, v8, 4, v95
	v_cvt_pk_bf16_f32 v9, v12, v145
	v_add_u32_e32 v10, v3, v8
	ds_write_b16 v10, v9 offset:40960
	v_cvt_pk_bf16_f32 v9, v13, v145
	ds_write_b16 v10, v9 offset:41104
	v_cvt_pk_bf16_f32 v9, v14, v145
	ds_write_b16 v10, v9 offset:41248
	v_cvt_pk_bf16_f32 v9, v15, v145
	ds_write_b16 v10, v9 offset:41392
	v_ashrrev_i32_e32 v9, 8, v171
	v_bitop3_b32 v9, v91, v9, 7 bitop3:0x6c
	v_lshl_or_b32 v9, v9, 4, v95
	v_cvt_pk_bf16_f32 v10, v16, v145
	v_add_u32_e32 v11, v3, v9
	ds_write_b16 v11, v10 offset:40960
	v_cvt_pk_bf16_f32 v10, v17, v145
	ds_write_b16 v11, v10 offset:41104
	v_cvt_pk_bf16_f32 v10, v18, v145
	ds_write_b16 v11, v10 offset:41248
	v_cvt_pk_bf16_f32 v10, v19, v145
	ds_write_b16 v11, v10 offset:41392
	v_ashrrev_i32_e32 v10, 8, v172
	v_bitop3_b32 v10, v91, v10, 7 bitop3:0x6c
	v_lshl_or_b32 v10, v10, 4, v95
	v_cvt_pk_bf16_f32 v11, v20, v145
	v_add_u32_e32 v3, v3, v10
	ds_write_b16 v3, v11 offset:40960
	v_cvt_pk_bf16_f32 v11, v21, v145
	ds_write_b16 v3, v11 offset:41104
	v_cvt_pk_bf16_f32 v11, v22, v145
	v_readlane_b32 s2, v254, 47
	ds_write_b16 v3, v11 offset:41248
	v_cvt_pk_bf16_f32 v11, v23, v145
	ds_write_b16 v3, v11 offset:41392
	v_add_u32_e32 v3, s2, v89
	v_mad_u32_u24 v4, v167, s0, v223
	v_mad_u32_u24 v11, v167, s0, v3
	v_mad_u32_u24 v5, v167, s0, v224
	ds_write_b16 v11, v28
	ds_write_b16_d16_hi v11, v28 offset:144
	v_add_u32_e32 v11, v3, v4
	v_add3_u32 v4, s2, v4, v89
	ds_write_b16_d16_hi v4, v29 offset:144
	v_add_u32_e32 v4, v3, v5
	v_mad_u32_u24 v6, v167, s0, v225
	ds_write_b16 v4, v30
	v_add3_u32 v4, s2, v5, v89
	ds_write_b16_d16_hi v4, v30 offset:144
	v_add_u32_e32 v4, v3, v6
	v_mad_u32_u24 v7, v167, s0, v226
	ds_write_b16 v4, v31
	v_add3_u32 v4, s2, v6, v89
	ds_write_b16_d16_hi v4, v31 offset:144
	v_add_u32_e32 v4, v3, v7
	v_mad_u32_u24 v0, v167, s0, v227
	ds_write_b16 v4, v24
	v_add3_u32 v4, s2, v7, v89
	v_mad_u32_u24 v1, v167, s0, v228
	ds_write_b16_d16_hi v4, v24 offset:144
	v_add_u32_e32 v4, v3, v0
	v_add3_u32 v0, s2, v0, v89
	ds_write_b16_d16_hi v0, v25 offset:144
	v_add_u32_e32 v0, v3, v1
	v_mad_u32_u24 v2, v167, s0, v229
	ds_write_b16 v0, v26
	v_add3_u32 v0, s2, v1, v89
	ds_write_b16_d16_hi v0, v26 offset:144
	v_add_u32_e32 v0, v3, v2
	ds_write_b16 v0, v27
	v_add3_u32 v0, s2, v2, v89
	v_readlane_b32 s2, v254, 48
	ds_write_b16_d16_hi v0, v27 offset:144
	v_cvt_pk_bf16_f32 v1, v64, v145
	ds_write_b16 v11, v29
	v_mov_b32_e32 v0, s2
	v_mad_u32_u24 v0, v168, s0, v0
	v_add_u32_e32 v2, v0, v93
	ds_write_b16 v4, v25
	ds_write_b16 v2, v1
	v_cvt_pk_bf16_f32 v1, v65, v145
	ds_write_b16 v2, v1 offset:144
	v_cvt_pk_bf16_f32 v1, v66, v145
	ds_write_b16 v2, v1 offset:288
	v_cvt_pk_bf16_f32 v1, v67, v145
	ds_write_b16 v2, v1 offset:432
	v_cvt_pk_bf16_f32 v1, v68, v145
	v_add_u32_e32 v2, v0, v8
	ds_write_b16 v2, v1
	v_cvt_pk_bf16_f32 v1, v69, v145
	ds_write_b16 v2, v1 offset:144
	v_cvt_pk_bf16_f32 v1, v70, v145
	ds_write_b16 v2, v1 offset:288
	v_cvt_pk_bf16_f32 v1, v71, v145
	ds_write_b16 v2, v1 offset:432
	v_cvt_pk_bf16_f32 v1, v72, v145
	v_add_u32_e32 v2, v0, v9
	ds_write_b16 v2, v1
	v_cvt_pk_bf16_f32 v1, v73, v145
	ds_write_b16 v2, v1 offset:144
	v_cvt_pk_bf16_f32 v1, v74, v145
	ds_write_b16 v2, v1 offset:288
	v_cvt_pk_bf16_f32 v1, v75, v145
	ds_write_b16 v2, v1 offset:432
	v_cvt_pk_bf16_f32 v1, v76, v145
	v_add_u32_e32 v0, v0, v10
	ds_write_b16 v0, v1
	v_cvt_pk_bf16_f32 v1, v77, v145
	ds_write_b16 v0, v1 offset:144
	v_cvt_pk_bf16_f32 v1, v78, v145
	ds_write_b16 v0, v1 offset:288
	v_cvt_pk_bf16_f32 v1, v79, v145
	ds_write_b16 v0, v1 offset:432
	s_waitcnt lgkmcnt(0)
	s_barrier
	v_mov_b32_e32 v2, 0
; #define LAS __attribute__((address_space(3)))
; DI float bf2f(unsigned v) { return __uint_as_float(v << 16); }
; DI bf16_t f2bf(float f) { return (bf16_t)(cvt_pk(f, 0.f) & 0xffffu); }
; template <bool FINAL>
; DI void gla_unit(KA a, int l, int item, LAS unsigned char* lds) {
;     ...
;     for (int hh = 0; hh < 2; ++hh) {
;         LAS float* gsum = (LAS float*)(lds + hh * GL_HEAD + GL_GSUM); LAS float* dS = (LAS float*)(lds + hh * GL_HEAD + GL_DS);
;         LAS bf16_t* qs = (LAS bf16_t*)(lds + hh * GL_HEAD + GL_QS); LAS bf16_t* ks = (LAS bf16_t*)(lds + hh * GL_HEAD + GL_KS);
;         float prefix = 0.f, blast = 0.f;
; #pragma unroll
;         for (int g2 = 0; g2 < 8; ++g2) { const float v = gsum[g2 * 64 + dk]; blast += v; if (g2 < tg) prefix += v; }
; #pragma unroll
;         for (int jj = 0; jj < 8; ++jj) {
;             const int t = 8 * tg + jj;
;             const float bj = prefix + bl[hh][jj];
;             const float kv = bf2f(kraw[hh][jj]);
;             if (FINAL) { qs[t * 72 + dk] = f2bf(bf2f(qraw[hh][jj]) * 0.125f * __expf(bj)); ks[t * 72 + dk] = f2bf(kv * __expf(-bj)); }
;             else ks[dk * 72 + t] = f2bf(kv * __expf(blast - bj));
;         }
.LBB0_916:
	v_add_f32_e32 v1, v86, v2
	v_mul_f32_e32 v0, 0x3fb8aa3b, v1
	v_exp_f32_e32 v0, v0
	v_mul_f32_e32 v1, 0xbfb8aa3b, v1
	v_exp_f32_e32 v1, v1
	s_mul_i32 s0, s43, 0x240
	v_mul_f32_e32 v0, v140, v0
	v_cvt_pk_bf16_f32 v3, v0, v145
	v_or_b32_e32 v0, s0, v85
	v_lshl_add_u32 v4, v0, 1, 0
	v_mul_f32_e32 v1, v139, v1
	ds_write_b16 v4, v3 offset:4096
	v_cvt_pk_bf16_f32 v1, v1, v145
	v_add_f32_e32 v3, v106, v2
	ds_write_b16 v4, v1 offset:13312
	v_mul_f32_e32 v1, 0x3fb8aa3b, v3
	v_exp_f32_e32 v1, v1
	v_mul_f32_e32 v3, 0xbfb8aa3b, v3
	v_exp_f32_e32 v3, v3
	s_mulk_i32 s45, 0x48
	v_mul_f32_e32 v1, v136, v1
	v_cvt_pk_bf16_f32 v4, v1, v145
	v_add_u32_e32 v1, s45, v85
	v_mul_f32_e32 v3, v137, v3
	v_lshl_add_u32 v5, v1, 1, 0
	v_cvt_pk_bf16_f32 v3, v3, v145
	ds_write_b16 v5, v3 offset:13312
	v_add_f32_e32 v3, v104, v2
	ds_write_b16 v5, v4 offset:4096
	v_mul_f32_e32 v4, 0x3fb8aa3b, v3
	v_mul_f32_e32 v3, 0xbfb8aa3b, v3
	v_exp_f32_e32 v3, v3
	v_exp_f32_e32 v4, v4
	s_add_i32 s0, 0, 0x10c00
	s_andn2_b64 vcc, exec, s[18:19]
	v_mul_f32_e32 v3, v134, v3
	v_mul_f32_e32 v4, v138, v4
	v_cvt_pk_bf16_f32 v3, v3, v145
	v_cvt_pk_bf16_f32 v4, v4, v145
	ds_write_b16 v5, v3 offset:13456
	v_add_f32_e32 v3, v102, v2
	ds_write_b16 v5, v4 offset:4240
	v_mul_f32_e32 v4, 0x3fb8aa3b, v3
	v_mul_f32_e32 v3, 0xbfb8aa3b, v3
	v_exp_f32_e32 v3, v3
	v_exp_f32_e32 v4, v4
	v_mul_f32_e32 v3, v133, v3
	v_mul_f32_e32 v4, v132, v4
	v_cvt_pk_bf16_f32 v3, v3, v145
	v_cvt_pk_bf16_f32 v4, v4, v145
	ds_write_b16 v5, v3 offset:13600
	v_add_f32_e32 v3, v100, v2
	ds_write_b16 v5, v4 offset:4384
	v_mul_f32_e32 v4, 0x3fb8aa3b, v3
	v_mul_f32_e32 v3, 0xbfb8aa3b, v3
	v_exp_f32_e32 v3, v3
	v_exp_f32_e32 v4, v4
	v_mul_f32_e32 v3, v130, v3
	v_mul_f32_e32 v4, v135, v4
	v_cvt_pk_bf16_f32 v3, v3, v145
	v_cvt_pk_bf16_f32 v4, v4, v145
	ds_write_b16 v5, v3 offset:13744
	v_add_f32_e32 v3, v98, v2
	ds_write_b16 v5, v4 offset:4528
	v_mul_f32_e32 v4, 0x3fb8aa3b, v3
	v_mul_f32_e32 v3, 0xbfb8aa3b, v3
	v_exp_f32_e32 v3, v3
	v_exp_f32_e32 v4, v4
	v_mul_f32_e32 v3, v129, v3
	v_mul_f32_e32 v4, v128, v4
	v_cvt_pk_bf16_f32 v3, v3, v145
	v_cvt_pk_bf16_f32 v4, v4, v145
	ds_write_b16 v5, v3 offset:13888
	v_add_f32_e32 v3, v96, v2
	ds_write_b16 v5, v4 offset:4672
	v_mul_f32_e32 v4, 0x3fb8aa3b, v3
	v_mul_f32_e32 v3, 0xbfb8aa3b, v3
	v_exp_f32_e32 v3, v3
	v_add_f32_e32 v2, v83, v2
	v_exp_f32_e32 v4, v4
	v_mul_f32_e32 v3, v127, v3
	v_cvt_pk_bf16_f32 v3, v3, v145
	ds_write_b16 v5, v3 offset:14032
	v_mul_f32_e32 v3, 0x3fb8aa3b, v2
	v_exp_f32_e32 v3, v3
	v_mul_f32_e32 v2, 0xbfb8aa3b, v2
	v_exp_f32_e32 v2, v2
	v_mul_f32_e32 v4, v131, v4
	v_mul_f32_e32 v3, v125, v3
	v_cvt_pk_bf16_f32 v3, v3, v145
	ds_write_b16 v5, v3 offset:4960
	v_mul_f32_e32 v2, v126, v2
	v_lshl_add_u32 v3, v85, 2, s0
	v_cvt_pk_bf16_f32 v4, v4, v145
	ds_write_b16 v5, v4 offset:4816
	v_cvt_pk_bf16_f32 v2, v2, v145
	ds_write_b16 v5, v2 offset:14176
	v_mov_b32_e32 v2, 0

; DI float bf2f(unsigned v) { return __uint_as_float(v << 16); }
; template <bool FINAL>
; DI void lru_unit(KA a, int l, int unit, LAS unsigned char* lds) {
;     ...
;         float xm3 = 0.f, xm2 = 0.f, xm1 = 0.f;
;         if (u.prompt) { if (u.c > 0) { xm3 = bf2f(U[(size_t)(row0 - 3) * UN + ch]); xm2 = bf2f(U[(size_t)(row0 - 2) * UN + ch]); xm1 = bf2f(U[(size_t)(row0 - 1) * UN + ch]); } }
;         else { const float* cs = a->in[3] + ((size_t)(l * NSB + u.s) * 3) * DLRU + ch; xm3 = cs[0]; xm2 = cs[DLRU]; xm1 = cs[2 * DLRU]; }
.LBB0_960:
	s_mov_b64 s[6:7], 0x11a8000
	s_andn2_b64 vcc, exec, s[8:9]
	s_waitcnt vmcnt(1)
	v_mov_b32_e32 v8, v7
	s_cbranch_vccnz .LBB0_967
	s_cmp_lt_i32 s94, 1
	s_cbranch_scc1 .LBB0_965
	s_mul_i32 s8, s13, 0x1600
	s_add_i32 s6, s13, -3
	s_mul_hi_i32 s7, s6, 0x1600
	s_add_i32 s6, s8, 0xffffbe00
	s_add_u32 s6, s4, s6
	s_addc_u32 s7, s5, s7
	v_lshlrev_b64 v[6:7], 1, v[4:5]
	s_waitcnt vmcnt(0)
	v_lshl_add_u64 v[8:9], s[6:7], 0, v[6:7]
	s_add_i32 s6, s13, -2
	s_mul_hi_i32 s7, s6, 0x1600
	s_add_i32 s6, s8, 0xffffd400
	s_add_u32 s6, s4, s6
	s_addc_u32 s7, s5, s7
	v_lshl_add_u64 v[10:11], s[6:7], 0, v[6:7]
	s_add_i32 s6, s13, -1
	s_addk_i32 s8, 0xea00
	s_mul_hi_i32 s7, s6, 0x1600
	s_add_u32 s6, s4, s8
	s_addc_u32 s7, s5, s7
	v_lshl_add_u64 v[6:7], s[6:7], 0, v[6:7]
	global_load_ushort v8, v[8:9], off
	s_nop 0
	global_load_ushort v9, v[10:11], off
	s_nop 0
	global_load_ushort v7, v[6:7], off
	s_waitcnt vmcnt(2)
	v_lshlrev_b32_e32 v6, 16, v8
	s_waitcnt vmcnt(1)
	v_lshlrev_b32_e32 v8, 16, v9
	s_waitcnt vmcnt(0)
	v_lshlrev_b32_e32 v9, 16, v7
	v_mov_b32_e32 v7, v8
	s_branch .LBB0_966
.LBB0_965:
	s_waitcnt vmcnt(0)
	v_mov_b32_e32 v9, 0
	v_mov_b32_e32 v8, v9
	v_mov_b32_e32 v7, v9
	v_mov_b32_e32 v6, v9

; template <class Epi, class Sched, bool ALIGN_EPI = false, bool SP2 = false>
; __device__ __forceinline__ void gemm_phase(PG8_LAS unsigned char* lds, const Gemm g, const Sched& S, const Epi& E) {
;     ...
;         const char* nA = has_next ? (const char*)g.A + (size_t)nxt.pm * tstep + (size_t)nxt.kt0 * kstep : cA; const char* nB = has_next ? (const char*)g.Bt + (size_t)nxt.pn * tstep + (size_t)nxt.kt0 * kstep : cB;
;     ...
;         for (int a = 0; a < 2; ++a)
; #pragma unroll
;             for (int b = 0; b < 2; ++b)
; #pragma unroll
;                 for (int m = 0; m < 4; ++m)
; #pragma unroll
;                     for (int n = 0; n < 2; ++n) acc[a][b][m][n] = (f32x4){0.f, 0.f, 0.f, 0.f};
.LBB0_1132:
	s_add_i32 s19, s35, -2
	s_add_u32 s21, s40, 0x100
	s_addc_u32 s31, s41, 0
	s_add_u32 s16, s38, 0x40080
	v_mov_b32_e32 v0, 0
	s_addc_u32 s17, s39, 0
	s_mov_b32 s38, 0
	v_mov_b64_e32 v[0:1], 0
	v_mov_b64_e32 v[2:3], 0
	v_mov_b64_e32 v[4:5], 0
	v_mov_b64_e32 v[6:7], 0
	v_mov_b64_e32 v[8:9], 0
	v_mov_b64_e32 v[10:11], 0
	v_mov_b64_e32 v[12:13], 0
	v_mov_b64_e32 v[14:15], 0
	v_mov_b64_e32 v[16:17], 0
	v_mov_b64_e32 v[18:19], 0
	v_mov_b64_e32 v[20:21], 0
	v_mov_b64_e32 v[22:23], 0
	v_mov_b64_e32 v[24:25], 0
	v_mov_b64_e32 v[26:27], 0
	v_mov_b64_e32 v[28:29], 0
	v_mov_b64_e32 v[30:31], 0
	v_mov_b64_e32 v[32:33], 0
	v_mov_b64_e32 v[34:35], 0
	v_mov_b64_e32 v[36:37], 0
	v_mov_b64_e32 v[38:39], 0
	v_mov_b64_e32 v[40:41], 0
	v_mov_b64_e32 v[42:43], 0
	v_mov_b64_e32 v[44:45], 0
	v_mov_b64_e32 v[46:47], 0
	v_mov_b64_e32 v[48:49], 0
	v_mov_b64_e32 v[50:51], 0
	v_mov_b64_e32 v[52:53], 0
	v_mov_b64_e32 v[54:55], 0
	v_mov_b64_e32 v[56:57], 0
	v_mov_b64_e32 v[58:59], 0
	v_mov_b64_e32 v[60:61], 0
	v_mov_b64_e32 v[62:63], 0
	v_mov_b64_e32 v[64:65], 0
	v_mov_b64_e32 v[66:67], 0
	v_mov_b64_e32 v[68:69], 0
	v_mov_b64_e32 v[70:71], 0
	v_mov_b64_e32 v[72:73], 0
	v_mov_b64_e32 v[74:75], 0
	v_mov_b64_e32 v[76:77], 0
	v_mov_b64_e32 v[78:79], 0
	v_mov_b64_e32 v[80:81], 0
	v_mov_b64_e32 v[82:83], 0
	v_mov_b64_e32 v[84:85], 0
	v_mov_b64_e32 v[86:87], 0
	v_mov_b64_e32 v[88:89], 0
	v_mov_b64_e32 v[90:91], 0
	v_mov_b64_e32 v[92:93], 0
	v_mov_b64_e32 v[94:95], 0
	v_mov_b64_e32 v[96:97], 0
	v_mov_b64_e32 v[98:99], 0
	v_mov_b64_e32 v[100:101], 0
	v_mov_b64_e32 v[102:103], 0
	v_mov_b64_e32 v[104:105], 0
	v_mov_b64_e32 v[106:107], 0
	v_mov_b64_e32 v[108:109], 0
	v_mov_b64_e32 v[110:111], 0
	v_mov_b64_e32 v[112:113], 0
	v_mov_b64_e32 v[114:115], 0
	v_mov_b64_e32 v[116:117], 0
	v_mov_b64_e32 v[118:119], 0
	v_mov_b64_e32 v[120:121], 0
	s_waitcnt vmcnt(0)
	v_mov_b32_e32 v122, v0
	v_mov_b32_e32 v123, v0
	v_mov_b32_e32 v124, v0
	v_mov_b32_e32 v125, v0
	v_mov_b32_e32 v126, v0
	v_mov_b32_e32 v127, v0
	s_mov_b64 s[66:67], 0x80

; template <class Epi, class Sched, bool ALIGN_EPI = false, bool SP2 = false>
; __device__ __forceinline__ void gemm_phase(PG8_LAS unsigned char* lds, const Gemm g, const Sched& S, const Epi& E) {
;     ...
;         for (int a = 0; a < 2; ++a)
; #pragma unroll
;             for (int b = 0; b < 2; ++b)
; #pragma unroll
;                 for (int m = 0; m < 4; ++m)
; #pragma unroll
;                     for (int n = 0; n < 2; ++n) acc[a][b][m][n] = (f32x4){0.f, 0.f, 0.f, 0.f};
.LBB0_1149:
	v_mov_b32_e32 v127, 0
	v_mov_b32_e32 v126, v127
	v_mov_b32_e32 v125, v127
	v_mov_b32_e32 v124, v127
	v_mov_b32_e32 v123, v127
	s_waitcnt vmcnt(0)
	v_mov_b32_e32 v122, 0
	v_mov_b64_e32 v[120:121], 0
	v_mov_b64_e32 v[118:119], 0
	v_mov_b64_e32 v[116:117], 0
	v_mov_b64_e32 v[114:115], 0
	v_mov_b64_e32 v[112:113], 0
	v_mov_b64_e32 v[110:111], 0
	v_mov_b64_e32 v[108:109], 0
	v_mov_b64_e32 v[106:107], 0
	v_mov_b64_e32 v[104:105], 0
	v_mov_b64_e32 v[102:103], 0
	v_mov_b64_e32 v[100:101], 0
	v_mov_b64_e32 v[98:99], 0
	v_mov_b64_e32 v[96:97], 0
	v_mov_b64_e32 v[94:95], 0
	v_mov_b64_e32 v[92:93], 0
	v_mov_b64_e32 v[90:91], 0
	v_mov_b64_e32 v[88:89], 0
	v_mov_b64_e32 v[86:87], 0
	v_mov_b64_e32 v[84:85], 0
	v_mov_b64_e32 v[82:83], 0
	v_mov_b64_e32 v[80:81], 0
	v_mov_b64_e32 v[78:79], 0
	v_mov_b64_e32 v[76:77], 0
	v_mov_b64_e32 v[74:75], 0
	v_mov_b64_e32 v[72:73], 0
	v_mov_b64_e32 v[70:71], 0
	v_mov_b64_e32 v[68:69], 0
	v_mov_b64_e32 v[66:67], 0
	v_mov_b64_e32 v[64:65], 0
	v_mov_b64_e32 v[62:63], 0
	v_mov_b64_e32 v[60:61], 0
	v_mov_b64_e32 v[58:59], 0
	v_mov_b64_e32 v[56:57], 0
	v_mov_b64_e32 v[54:55], 0
	v_mov_b64_e32 v[52:53], 0
	v_mov_b64_e32 v[50:51], 0
	v_mov_b64_e32 v[48:49], 0
	v_mov_b64_e32 v[46:47], 0
	v_mov_b64_e32 v[44:45], 0
	v_mov_b64_e32 v[42:43], 0
	v_mov_b64_e32 v[40:41], 0
	v_mov_b64_e32 v[38:39], 0
	v_mov_b64_e32 v[36:37], 0
	v_mov_b64_e32 v[34:35], 0
	v_mov_b64_e32 v[32:33], 0
	v_mov_b64_e32 v[30:31], 0
	v_mov_b64_e32 v[28:29], 0
	v_mov_b64_e32 v[26:27], 0
	v_mov_b64_e32 v[24:25], 0
	v_mov_b64_e32 v[22:23], 0
	v_mov_b64_e32 v[20:21], 0
	v_mov_b64_e32 v[18:19], 0
	v_mov_b64_e32 v[16:17], 0
	v_mov_b64_e32 v[14:15], 0
	v_mov_b64_e32 v[12:13], 0
	v_mov_b64_e32 v[10:11], 0
	v_mov_b64_e32 v[8:9], 0
	v_mov_b64_e32 v[6:7], 0
	v_mov_b64_e32 v[4:5], 0
	v_mov_b64_e32 v[2:3], 0
	v_mov_b64_e32 v[0:1], 0
	s_and_b64 vcc, exec, s[24:25]
	s_cbranch_vccnz .LBB0_1135
	s_branch .LBB0_1136

; template <class Epi, class Sched, bool ALIGN_EPI = false, bool SP2 = false>
; __device__ __forceinline__ void gemm_phase(PG8_LAS unsigned char* lds, const Gemm g, const Sched& S, const Epi& E) {
;     ...
;         const bool has_next = S.next(ui + 1, nxt);
;         const char* nA = has_next ? (const char*)g.A + (size_t)nxt.pm * tstep + (size_t)nxt.kt0 * kstep : cA; const char* nB = has_next ? (const char*)g.Bt + (size_t)nxt.pn * tstep + (size_t)nxt.kt0 * kstep : cB;
;     ...
; #pragma unroll
;         for (int a = 0; a < 2; ++a)
; #pragma unroll
;             for (int b = 0; b < 2; ++b)
; #pragma unroll
;                 for (int m = 0; m < 4; ++m)
; #pragma unroll
;                     for (int n = 0; n < 2; ++n) acc[a][b][m][n] = (f32x4){0.f, 0.f, 0.f, 0.f};
;         cur = nxt; cA = nA; cB = nB; ++ui;
.LBB0_1204:
	s_ashr_i32 s17, s16, 31
	s_lshl_b64 s[18:19], s[16:17], 19
	s_add_u32 s18, s44, s18
	s_addc_u32 s19, s45, s19
	s_and_b64 s[20:21], s[12:13], exec
	s_cselect_b32 s17, s19, s29
	s_cselect_b32 s23, s18, s28
	s_ashr_i32 s15, s14, 31
	s_lshl_b64 s[20:21], s[14:15], 19
	s_add_u32 s20, s46, s20
	s_addc_u32 s21, s47, s21
	s_and_b64 s[30:31], s[12:13], exec
	s_cselect_b32 s15, s21, s27
	s_cselect_b32 s42, s20, s26
	s_add_u32 s43, s26, 0x100
	s_addc_u32 s48, s27, 0
	s_add_u32 s26, s28, 0x40080
	v_mov_b32_e32 v0, 0
	s_addc_u32 s27, s29, 0
	s_mov_b32 s49, -2
	s_waitcnt lgkmcnt(0)
	v_mov_b64_e32 v[0:1], 0
	v_mov_b64_e32 v[2:3], 0
	v_mov_b64_e32 v[4:5], 0
	v_mov_b64_e32 v[6:7], 0
	v_mov_b64_e32 v[16:17], 0
	v_mov_b64_e32 v[18:19], 0
	v_mov_b64_e32 v[20:21], 0
	v_mov_b64_e32 v[22:23], 0
	v_mov_b64_e32 v[32:33], 0
	v_mov_b64_e32 v[34:35], 0
	v_mov_b64_e32 v[36:37], 0
	v_mov_b64_e32 v[38:39], 0
	v_mov_b64_e32 v[48:49], 0
	v_mov_b64_e32 v[50:51], 0
	v_mov_b64_e32 v[52:53], 0
	v_mov_b64_e32 v[54:55], 0
	v_mov_b64_e32 v[8:9], 0
	v_mov_b64_e32 v[10:11], 0
	v_mov_b64_e32 v[12:13], 0
	v_mov_b64_e32 v[14:15], 0
	v_mov_b64_e32 v[24:25], 0
	v_mov_b64_e32 v[26:27], 0
	v_mov_b64_e32 v[28:29], 0
	v_mov_b64_e32 v[30:31], 0
	v_mov_b64_e32 v[40:41], 0
	v_mov_b64_e32 v[42:43], 0
	v_mov_b64_e32 v[44:45], 0
	v_mov_b64_e32 v[46:47], 0
	v_mov_b64_e32 v[56:57], 0
	v_mov_b64_e32 v[58:59], 0
	v_mov_b64_e32 v[60:61], 0
	v_mov_b64_e32 v[62:63], 0
	v_mov_b64_e32 v[64:65], 0
	v_mov_b64_e32 v[66:67], 0
	v_mov_b64_e32 v[68:69], 0
	v_mov_b64_e32 v[70:71], 0
	v_mov_b64_e32 v[80:81], 0
	v_mov_b64_e32 v[82:83], 0
	v_mov_b64_e32 v[84:85], 0
	v_mov_b64_e32 v[86:87], 0
	v_mov_b64_e32 v[96:97], 0
	v_mov_b64_e32 v[98:99], 0
	v_mov_b64_e32 v[100:101], 0
	v_mov_b64_e32 v[102:103], 0
	v_mov_b64_e32 v[112:113], 0
	v_mov_b64_e32 v[114:115], 0
	v_mov_b64_e32 v[116:117], 0
	v_mov_b64_e32 v[118:119], 0
	v_mov_b64_e32 v[72:73], 0
	v_mov_b64_e32 v[74:75], 0
	v_mov_b64_e32 v[76:77], 0
	v_mov_b64_e32 v[78:79], 0
	v_mov_b64_e32 v[88:89], 0
	v_mov_b64_e32 v[90:91], 0
	v_mov_b64_e32 v[92:93], 0
	v_mov_b64_e32 v[94:95], 0
	v_mov_b64_e32 v[104:105], 0
	v_mov_b64_e32 v[106:107], 0
	v_mov_b64_e32 v[108:109], 0
	v_mov_b64_e32 v[110:111], 0
	v_mov_b64_e32 v[120:121], 0
	s_waitcnt vmcnt(0)
	v_mov_b32_e32 v122, v0
	v_mov_b32_e32 v123, v0
	v_mov_b32_e32 v124, v0
	v_mov_b32_e32 v125, v0
	v_mov_b32_e32 v126, v0
	v_mov_b32_e32 v127, v0
	s_mov_b64 s[54:55], 0x80

; template <class Epi, class Sched, bool ALIGN_EPI = false, bool SP2 = false>
; __device__ __forceinline__ void gemm_phase(PG8_LAS unsigned char* lds, const Gemm g, const Sched& S, const Epi& E) {
;     ...
;         const bool has_next = S.next(ui + 1, nxt);
;         const char* nA = has_next ? (const char*)g.A + (size_t)nxt.pm * tstep + (size_t)nxt.kt0 * kstep : cA; const char* nB = has_next ? (const char*)g.Bt + (size_t)nxt.pn * tstep + (size_t)nxt.kt0 * kstep : cB;
;     ...
; #pragma unroll
;         for (int a = 0; a < 2; ++a)
; #pragma unroll
;             for (int b = 0; b < 2; ++b)
; #pragma unroll
;                 for (int m = 0; m < 4; ++m)
; #pragma unroll
;                     for (int n = 0; n < 2; ++n) acc[a][b][m][n] = (f32x4){0.f, 0.f, 0.f, 0.f};
;         cur = nxt; cA = nA; cB = nB; ++ui;
.LBB0_1294:
	s_ashr_i32 s17, s16, 31
	s_lshl_b64 s[18:19], s[16:17], 19
	s_add_u32 s18, s0, s18
	s_addc_u32 s19, s28, s19
	s_and_b64 s[20:21], s[6:7], exec
	s_cselect_b32 s17, s19, s25
	s_cselect_b32 s42, s18, s24
	s_ashr_i32 s15, s14, 31
	s_lshl_b64 s[20:21], s[14:15], 19
	s_add_u32 s20, s29, s20
	s_addc_u32 s21, s30, s21
	s_and_b64 s[26:27], s[6:7], exec
	s_cselect_b32 s15, s21, s23
	s_cselect_b32 s43, s20, s22
	s_add_u32 s44, s22, 0x100
	s_addc_u32 s45, s23, 0
	s_add_u32 s22, s24, 0x40080
	v_mov_b32_e32 v0, 0
	s_addc_u32 s23, s25, 0
	s_mov_b32 s46, -2
	v_mov_b64_e32 v[0:1], 0
	v_mov_b64_e32 v[2:3], 0
	v_mov_b64_e32 v[8:9], 0
	v_mov_b64_e32 v[10:11], 0
	v_mov_b64_e32 v[16:17], 0
	v_mov_b64_e32 v[18:19], 0
	v_mov_b64_e32 v[24:25], 0
	v_mov_b64_e32 v[26:27], 0
	v_mov_b64_e32 v[32:33], 0
	v_mov_b64_e32 v[34:35], 0
	v_mov_b64_e32 v[40:41], 0
	v_mov_b64_e32 v[42:43], 0
	v_mov_b64_e32 v[48:49], 0
	v_mov_b64_e32 v[50:51], 0
	v_mov_b64_e32 v[56:57], 0
	v_mov_b64_e32 v[58:59], 0
	v_mov_b64_e32 v[4:5], 0
	v_mov_b64_e32 v[6:7], 0
	v_mov_b64_e32 v[12:13], 0
	v_mov_b64_e32 v[14:15], 0
	v_mov_b64_e32 v[20:21], 0
	v_mov_b64_e32 v[22:23], 0
	v_mov_b64_e32 v[28:29], 0
	v_mov_b64_e32 v[30:31], 0
	v_mov_b64_e32 v[36:37], 0
	v_mov_b64_e32 v[38:39], 0
	v_mov_b64_e32 v[44:45], 0
	v_mov_b64_e32 v[46:47], 0
	v_mov_b64_e32 v[52:53], 0
	v_mov_b64_e32 v[54:55], 0
	v_mov_b64_e32 v[60:61], 0
	v_mov_b64_e32 v[62:63], 0
	v_mov_b64_e32 v[64:65], 0
	v_mov_b64_e32 v[66:67], 0
	v_mov_b64_e32 v[72:73], 0
	v_mov_b64_e32 v[74:75], 0
	v_mov_b64_e32 v[80:81], 0
	v_mov_b64_e32 v[82:83], 0
	v_mov_b64_e32 v[88:89], 0
	v_mov_b64_e32 v[90:91], 0
	v_mov_b64_e32 v[96:97], 0
	v_mov_b64_e32 v[98:99], 0
	v_mov_b64_e32 v[104:105], 0
	v_mov_b64_e32 v[106:107], 0
	v_mov_b64_e32 v[112:113], 0
	v_mov_b64_e32 v[114:115], 0
	v_mov_b64_e32 v[120:121], 0
	v_mov_b64_e32 v[122:123], 0
	v_mov_b64_e32 v[68:69], 0
	v_mov_b64_e32 v[70:71], 0
	v_mov_b64_e32 v[76:77], 0
	v_mov_b64_e32 v[78:79], 0
	v_mov_b64_e32 v[84:85], 0
	v_mov_b64_e32 v[86:87], 0
	v_mov_b64_e32 v[92:93], 0
	v_mov_b64_e32 v[94:95], 0
	v_mov_b64_e32 v[100:101], 0
	v_mov_b64_e32 v[102:103], 0
	v_mov_b64_e32 v[108:109], 0
	v_mov_b64_e32 v[110:111], 0
	v_mov_b64_e32 v[116:117], 0
	v_mov_b64_e32 v[118:119], 0
	v_mov_b64_e32 v[124:125], 0
	v_mov_b64_e32 v[126:127], 0
	s_mov_b64 s[52:53], 0x80

; template <class Epi, class Sched, bool ALIGN_EPI = false, bool SP2 = false>
; __device__ __forceinline__ void gemm_phase(PG8_LAS unsigned char* lds, const Gemm g, const Sched& S, const Epi& E) {
;     ...
; #pragma unroll
;         for (int a = 0; a < 2; ++a)
; #pragma unroll
;             for (int b = 0; b < 2; ++b)
; #pragma unroll
;                 for (int m = 0; m < 4; ++m)
; #pragma unroll
;                     for (int n = 0; n < 2; ++n) acc[a][b][m][n] = (f32x4){0.f, 0.f, 0.f, 0.f};
;         cur = nxt; cA = nA; cB = nB; ++ui;
.LBB0_1377:
	s_add_i32 s25, s27, -2
	s_add_u32 s57, s34, 0x100
	v_mov_b32_e32 v0, 0
	s_addc_u32 s58, s35, 0
	s_mov_b32 s34, 0
	v_mov_b64_e32 v[0:1], 0
	v_mov_b64_e32 v[2:3], 0
	v_mov_b64_e32 v[4:5], 0
	v_mov_b64_e32 v[6:7], 0
	v_mov_b64_e32 v[8:9], 0
	v_mov_b64_e32 v[10:11], 0
	v_mov_b64_e32 v[12:13], 0
	v_mov_b64_e32 v[14:15], 0
	v_mov_b64_e32 v[16:17], 0
	v_mov_b64_e32 v[18:19], 0
	v_mov_b64_e32 v[20:21], 0
	v_mov_b64_e32 v[22:23], 0
	v_mov_b64_e32 v[24:25], 0
	v_mov_b64_e32 v[26:27], 0
	v_mov_b64_e32 v[28:29], 0
	v_mov_b64_e32 v[30:31], 0
	v_mov_b64_e32 v[32:33], 0
	v_mov_b64_e32 v[34:35], 0
	v_mov_b64_e32 v[36:37], 0
	v_mov_b64_e32 v[38:39], 0
	v_mov_b64_e32 v[40:41], 0
	v_mov_b64_e32 v[42:43], 0
	v_mov_b64_e32 v[44:45], 0
	v_mov_b64_e32 v[46:47], 0
	v_mov_b64_e32 v[48:49], 0
	v_mov_b64_e32 v[50:51], 0
	v_mov_b64_e32 v[52:53], 0
	v_mov_b64_e32 v[54:55], 0
	v_mov_b64_e32 v[56:57], 0
	v_mov_b64_e32 v[58:59], 0
	v_mov_b64_e32 v[60:61], 0
	v_mov_b64_e32 v[62:63], 0
	v_mov_b64_e32 v[64:65], 0
	v_mov_b64_e32 v[66:67], 0
	v_mov_b64_e32 v[68:69], 0
	v_mov_b64_e32 v[70:71], 0
	v_mov_b64_e32 v[72:73], 0
	v_mov_b64_e32 v[74:75], 0
	v_mov_b64_e32 v[76:77], 0
	v_mov_b64_e32 v[78:79], 0
	v_mov_b64_e32 v[80:81], 0
	v_mov_b64_e32 v[82:83], 0
	v_mov_b64_e32 v[84:85], 0
	v_mov_b64_e32 v[86:87], 0
	v_mov_b64_e32 v[88:89], 0
	v_mov_b64_e32 v[90:91], 0
	v_mov_b64_e32 v[92:93], 0
	v_mov_b64_e32 v[94:95], 0
	v_mov_b64_e32 v[96:97], 0
	v_mov_b64_e32 v[98:99], 0
	v_mov_b64_e32 v[100:101], 0
	v_mov_b64_e32 v[102:103], 0
	v_mov_b64_e32 v[104:105], 0
	v_mov_b64_e32 v[106:107], 0
	v_mov_b64_e32 v[108:109], 0
	v_mov_b64_e32 v[110:111], 0
	v_mov_b64_e32 v[112:113], 0
	v_mov_b64_e32 v[114:115], 0
	v_mov_b64_e32 v[116:117], 0
	v_mov_b64_e32 v[118:119], 0
	v_mov_b64_e32 v[120:121], 0
	v_mov_b64_e32 v[122:123], 0
	v_mov_b64_e32 v[124:125], 0
	v_mov_b64_e32 v[126:127], 0
	s_mov_b64 s[62:63], 0x80

; template <class Epi, class Sched, bool ALIGN_EPI = false, bool SP2 = false>
; __device__ __forceinline__ void gemm_phase(PG8_LAS unsigned char* lds, const Gemm g, const Sched& S, const Epi& E) {
;     ...
; #pragma unroll
;         for (int a = 0; a < 2; ++a)
; #pragma unroll
;             for (int b = 0; b < 2; ++b)
; #pragma unroll
;                 for (int m = 0; m < 4; ++m)
; #pragma unroll
;                     for (int n = 0; n < 2; ++n) acc[a][b][m][n] = (f32x4){0.f, 0.f, 0.f, 0.f};
;         cur = nxt; cA = nA; cB = nB; ++ui;
.LBB0_1453:
	s_add_u32 s42, s18, 0x100
	v_mov_b32_e32 v0, 0
	s_addc_u32 s43, s19, 0
	s_mov_b32 s44, -2
	s_waitcnt lgkmcnt(0)
	v_mov_b64_e32 v[0:1], 0
	v_mov_b64_e32 v[2:3], 0
	v_mov_b64_e32 v[4:5], 0
	v_mov_b64_e32 v[6:7], 0
	v_mov_b64_e32 v[16:17], 0
	v_mov_b64_e32 v[18:19], 0
	v_mov_b64_e32 v[20:21], 0
	v_mov_b64_e32 v[22:23], 0
	v_mov_b64_e32 v[32:33], 0
	v_mov_b64_e32 v[34:35], 0
	v_mov_b64_e32 v[36:37], 0
	v_mov_b64_e32 v[38:39], 0
	v_mov_b64_e32 v[48:49], 0
	v_mov_b64_e32 v[50:51], 0
	v_mov_b64_e32 v[52:53], 0
	v_mov_b64_e32 v[54:55], 0
	v_mov_b64_e32 v[8:9], 0
	v_mov_b64_e32 v[10:11], 0
	v_mov_b64_e32 v[12:13], 0
	v_mov_b64_e32 v[14:15], 0
	v_mov_b64_e32 v[24:25], 0
	v_mov_b64_e32 v[26:27], 0
	v_mov_b64_e32 v[28:29], 0
	v_mov_b64_e32 v[30:31], 0
	v_mov_b64_e32 v[40:41], 0
	v_mov_b64_e32 v[42:43], 0
	v_mov_b64_e32 v[44:45], 0
	v_mov_b64_e32 v[46:47], 0
	v_mov_b64_e32 v[56:57], 0
	v_mov_b64_e32 v[58:59], 0
	v_mov_b64_e32 v[60:61], 0
	v_mov_b64_e32 v[62:63], 0
	v_mov_b64_e32 v[64:65], 0
	v_mov_b64_e32 v[66:67], 0
	v_mov_b64_e32 v[68:69], 0
	v_mov_b64_e32 v[70:71], 0
	v_mov_b64_e32 v[80:81], 0
	v_mov_b64_e32 v[82:83], 0
	v_mov_b64_e32 v[84:85], 0
	v_mov_b64_e32 v[86:87], 0
	v_mov_b64_e32 v[96:97], 0
	v_mov_b64_e32 v[98:99], 0
	v_mov_b64_e32 v[100:101], 0
	v_mov_b64_e32 v[102:103], 0
	v_mov_b64_e32 v[112:113], 0
	v_mov_b64_e32 v[114:115], 0
	v_mov_b64_e32 v[116:117], 0
	v_mov_b64_e32 v[118:119], 0
	v_mov_b64_e32 v[72:73], 0
	v_mov_b64_e32 v[74:75], 0
	v_mov_b64_e32 v[76:77], 0
	v_mov_b64_e32 v[78:79], 0
	v_mov_b64_e32 v[88:89], 0
	v_mov_b64_e32 v[90:91], 0
	v_mov_b64_e32 v[92:93], 0
	v_mov_b64_e32 v[94:95], 0
	v_mov_b64_e32 v[104:105], 0
	v_mov_b64_e32 v[106:107], 0
	v_mov_b64_e32 v[108:109], 0
	v_mov_b64_e32 v[110:111], 0
	v_mov_b64_e32 v[120:121], 0
	v_mov_b64_e32 v[122:123], 0
	v_mov_b64_e32 v[124:125], 0
	v_mov_b64_e32 v[126:127], 0
	s_mov_b64 s[48:49], 0x80
